# GEMM K-loops (SwiGLU, PROJ even/odd): LDS-DMA loads use scalar base + 32-bit lane offset form, removing 16 64-bit VALU address adds per iteration per wave
# speedup vs baseline: 1.0081x; 1.0062x over previous
; #define PG8_WAIT_V(n) asm volatile("s_waitcnt vmcnt(" #n ")" ::: "memory")
; template <int EPI, bool ALIGN_EPI = true, bool SP2 = true>
; DI void gemm8_phase(const GemmArgs& g, char* lds_) {
;     ...
;   f32x4 acc[2][2][4][2];
; #pragma unroll
;   for (int a = 0; a < 2; ++a)
; #pragma unroll
;     for (int b = 0; b < 2; ++b)
; #pragma unroll
;       for (int m = 0; m < 4; ++m)
; #pragma unroll
;         for (int n = 0; n < 2; ++n) acc[a][b][m][n] = f32x4{0.f, 0.f, 0.f, 0.f};
;   bf16x8 At[4][2], B0[2][2], B1[2][2];
;   const char* cA = (const char*)g.A0 + (size_t)cpm * tstep;
;   const char* cB = (const char*)g.Bt0 + (size_t)cpn * tstep;
;   PG8_WAIT_V(0);
;   __syncthreads();
;   if constexpr (SP2) {
;     PG8_STAGE(PG8_SB(0, 0), cB); PG8_STAGE(PG8_SB(0, 1), cB + hstep); PG8_STAGE(PG8_SA(0, 0), cA); PG8_STAGE(PG8_SA(0, 1), cA + hstep);
;     if (wr == 1) PG8_BAR;
;     PG8_WAIT_V(2); PG8_BAR;
;     PG8_STAGE(PG8_SB(1, 0), cB + kstep); PG8_STAGE(PG8_SA(1, 0), cA + kstep); PG8_STAGE(PG8_SB(1, 1), cB + hstep + kstep);
;     PG8_WAIT_V(6); PG8_BAR;
;   } else {
;     PG8_STAGE(PG8_SB(0, 0), cB); PG8_STAGE(PG8_SA(0, 0), cA); PG8_STAGE(PG8_SB(0, 1), cB + hstep); PG8_STAGE(PG8_SA(0, 1), cA + hstep);
;     if (wr == 1) PG8_BAR;
;     PG8_WAIT_V(4); PG8_BAR;
;     PG8_STAGE(PG8_SB(1, 0), cB + kstep); PG8_STAGE(PG8_SA(1, 0), cA + kstep); PG8_STAGE(PG8_SB(1, 1), cB + hstep + kstep);
;     PG8_WAIT_V(6); PG8_BAR;
;   }
;   for (;;) {
;     const int nid = (int)blockIdx.x + (ui + 1) * G;
;     const bool has_next = nid < total;
;     if (has_next) tile_map(nid, g.NTm, g.NTn, npm, npn, g.gm);
;     const char* nA = has_next ? (const char*)g.A0 + (size_t)npm * tstep : cA;
;     const char* nB = has_next ? (const char*)g.Bt0 + (size_t)npn * tstep : cB;
; #pragma unroll 1
;     for (int t = 0; t < nt; t += 2) {
;       const bool last = (t == nt - 2);
;       const char* a1 = cA + (size_t)(t + 1) * kstep;
;       const char* a2 = last ? nA : cA + (size_t)(t + 2) * kstep;
;       const char* b2 = last ? nB : cB + (size_t)(t + 2) * kstep;
;       const char* a3 = a2 + kstep; const char* b3 = b2 + kstep;
;       if constexpr (SP2) {
;         const bool relax = EPI_VM > 0 && t == 0 && ui > 0;
;         PG8_LDB(B0, 0, 0); PG8_LDB(B1, 0, 1); PG8_SCHED; PG8_LDA(At, 0, 0); PG8_STAGE(PG8_SA(1, 1), a1 + hstep);
;         if (relax) PG8_WAIT_V(24); else PG8_WAIT_V(8);
.LBB0_291:
	s_ashr_i32 s43, s42, 31
	s_lshl_b64 s[22:23], s[42:43], 19
	s_add_u32 s48, s2, s22
	s_addc_u32 s49, s7, s23
	s_and_b64 s[22:23], s[46:47], exec
	s_cselect_b32 s22, s49, s85
	s_cselect_b32 s23, s48, s84
	s_add_u32 s41, s84, 0x100
	v_mov_b32_e32 v6, 0
	s_addc_u32 s43, s85, 0
	s_mov_b32 vcc_lo, -2
	v_mov_b32_e32 v7, v6
	v_mov_b32_e32 v8, v6
	v_mov_b32_e32 v9, v6
	v_mov_b32_e32 v2, v6
	v_mov_b32_e32 v3, v6
	v_mov_b32_e32 v4, v6
	v_mov_b32_e32 v5, v6
	v_mov_b32_e32 v14, v6
	v_mov_b32_e32 v15, v6
	v_mov_b32_e32 v16, v6
	v_mov_b32_e32 v17, v6
	v_mov_b32_e32 v10, v6
	v_mov_b32_e32 v11, v6
	v_mov_b32_e32 v12, v6
	v_mov_b32_e32 v13, v6
	v_mov_b32_e32 v22, v6
	v_mov_b32_e32 v23, v6
	v_mov_b32_e32 v24, v6
	v_mov_b32_e32 v25, v6
	v_mov_b32_e32 v18, v6
	v_mov_b32_e32 v19, v6
	v_mov_b32_e32 v20, v6
	v_mov_b32_e32 v21, v6
	v_mov_b32_e32 v30, v6
	v_mov_b32_e32 v31, v6
	v_mov_b32_e32 v32, v6
	v_mov_b32_e32 v33, v6
	v_mov_b32_e32 v26, v6
	v_mov_b32_e32 v27, v6
	v_mov_b32_e32 v28, v6
	v_mov_b32_e32 v29, v6
	v_mov_b32_e32 v38, v6
	v_mov_b32_e32 v39, v6
	v_mov_b32_e32 v40, v6
	v_mov_b32_e32 v41, v6
	v_mov_b32_e32 v34, v6
	v_mov_b32_e32 v35, v6
	v_mov_b32_e32 v36, v6
	v_mov_b32_e32 v37, v6
	v_mov_b32_e32 v46, v6
	v_mov_b32_e32 v47, v6
	v_mov_b32_e32 v48, v6
	v_mov_b32_e32 v49, v6
	v_mov_b32_e32 v42, v6
	v_mov_b32_e32 v43, v6
	v_mov_b32_e32 v44, v6
	v_mov_b32_e32 v45, v6
	v_mov_b32_e32 v54, v6
	v_mov_b32_e32 v55, v6
	v_mov_b32_e32 v56, v6
	v_mov_b32_e32 v57, v6
	v_mov_b32_e32 v50, v6
	v_mov_b32_e32 v51, v6
	v_mov_b32_e32 v52, v6
	v_mov_b32_e32 v53, v6
	v_mov_b32_e32 v62, v6
	v_mov_b32_e32 v63, v6
	v_mov_b32_e32 v64, v6
	v_mov_b32_e32 v65, v6
	v_mov_b32_e32 v58, v6
	v_mov_b32_e32 v59, v6
	v_mov_b32_e32 v60, v6
	v_mov_b32_e32 v61, v6
	v_mov_b32_e32 v70, v6
	v_mov_b32_e32 v71, v6
	v_mov_b32_e32 v72, v6
	v_mov_b32_e32 v73, v6
	v_mov_b32_e32 v66, v6
	v_mov_b32_e32 v67, v6
	v_mov_b32_e32 v68, v6
	v_mov_b32_e32 v69, v6
	v_mov_b32_e32 v78, v6
	v_mov_b32_e32 v79, v6
	v_mov_b32_e32 v80, v6
	v_mov_b32_e32 v81, v6
	v_mov_b32_e32 v74, v6
	v_mov_b32_e32 v75, v6
	v_mov_b32_e32 v76, v6
	v_mov_b32_e32 v77, v6
	v_mov_b32_e32 v86, v6
	v_mov_b32_e32 v87, v6
	v_mov_b32_e32 v88, v6
	v_mov_b32_e32 v89, v6
	v_mov_b32_e32 v82, v6
	v_mov_b32_e32 v83, v6
	v_mov_b32_e32 v84, v6
	v_mov_b32_e32 v85, v6
	v_mov_b32_e32 v94, v6
	v_mov_b32_e32 v95, v6
	v_mov_b32_e32 v96, v6
	v_mov_b32_e32 v97, v6
	v_mov_b32_e32 v90, v6
	v_mov_b32_e32 v91, v6
	v_mov_b32_e32 v92, v6
	v_mov_b32_e32 v93, v6
	v_mov_b32_e32 v102, v6
	v_mov_b32_e32 v103, v6
	v_mov_b32_e32 v104, v6
	v_mov_b32_e32 v105, v6
	v_mov_b32_e32 v98, v6
	v_mov_b32_e32 v99, v6
	v_mov_b32_e32 v100, v6
	v_mov_b32_e32 v101, v6
	v_mov_b32_e32 v110, v6
	v_mov_b32_e32 v111, v6
	v_mov_b32_e32 v112, v6
	v_mov_b32_e32 v113, v6
	v_mov_b32_e32 v106, v6
	v_mov_b32_e32 v107, v6
	v_mov_b32_e32 v108, v6
	v_mov_b32_e32 v109, v6
	v_mov_b32_e32 v118, v6
	v_mov_b32_e32 v119, v6
	v_mov_b32_e32 v120, v6
	v_mov_b32_e32 v121, v6
	v_mov_b32_e32 v114, v6
	v_mov_b32_e32 v115, v6
	v_mov_b32_e32 v116, v6
	v_mov_b32_e32 v117, v6
	v_mov_b32_e32 v126, v6
	v_mov_b32_e32 v127, v6
	v_mov_b32_e32 v128, v6
	v_mov_b32_e32 v129, v6
	v_mov_b32_e32 v122, v6
	v_mov_b32_e32 v123, v6
	v_mov_b32_e32 v124, v6
	v_mov_b32_e32 v125, v6
	v_add_u32_e32 v164, 0x80, v0
	v_add_u32_e32 v165, 0x80, v130
.LBB0_292:
	ds_read_b128 v[158:161], v141
	ds_read_b128 v[168:171], v142
	ds_read_b128 v[192:195], v143
	ds_read_b128 v[196:199], v144
	ds_read_b128 v[200:203], v145
	ds_read_b128 v[204:207], v146
	ds_read_b128 v[208:211], v147
	ds_read_b128 v[212:215], v148
	s_add_u32 s84, s34, 0x100
	s_addc_u32 s85, s35, 0
	s_cmp_eq_u32 vcc_lo, 12
	s_cselect_b32 s91, s45, s85
	s_cselect_b32 s90, s44, s84
	s_cselect_b32 s87, s22, s43
	s_cselect_b32 s86, s23, s41
	s_mov_b32 m0, s17
	ds_read_b128 v[216:219], v139
	ds_read_b128 v[220:223], v139 offset:1024
	ds_read_b128 v[224:227], v139 offset:2048
	ds_read_b128 v[228:231], v139 offset:3072
	ds_read_b128 v[232:235], v139 offset:4096
	ds_read_b128 v[236:239], v139 offset:5120
	ds_read_b128 v[240:243], v139 offset:6144
	ds_read_b128 v[244:247], v139 offset:7168
	global_load_lds_dwordx4 v132, s[34:35]
	s_mov_b32 m0, s16
	s_nop 0
	global_load_lds_dwordx4 v134, s[34:35]
	s_waitcnt vmcnt(8)
	s_waitcnt lgkmcnt(0)
	s_barrier
	s_setprio 1
	s_waitcnt lgkmcnt(0)
	v_mfma_f32_16x16x32_bf16 v[122:125], v[158:161], v[216:219], v[122:125]
	v_mfma_f32_16x16x32_bf16 v[126:129], v[192:195], v[216:219], v[126:129]
	v_mfma_f32_16x16x32_bf16 v[114:117], v[158:161], v[224:227], v[114:117]
	v_mfma_f32_16x16x32_bf16 v[118:121], v[192:195], v[224:227], v[118:121]
	v_mfma_f32_16x16x32_bf16 v[106:109], v[158:161], v[232:235], v[106:109]
	v_mfma_f32_16x16x32_bf16 v[110:113], v[192:195], v[232:235], v[110:113]
	v_mfma_f32_16x16x32_bf16 v[98:101], v[158:161], v[240:243], v[98:101]
	v_mfma_f32_16x16x32_bf16 v[102:105], v[192:195], v[240:243], v[102:105]
	v_mfma_f32_16x16x32_bf16 v[122:125], v[168:171], v[220:223], v[122:125]
	v_mfma_f32_16x16x32_bf16 v[126:129], v[196:199], v[220:223], v[126:129]
	v_mfma_f32_16x16x32_bf16 v[114:117], v[168:171], v[228:231], v[114:117]
	v_mfma_f32_16x16x32_bf16 v[118:121], v[196:199], v[228:231], v[118:121]
	v_mfma_f32_16x16x32_bf16 v[106:109], v[168:171], v[236:239], v[106:109]
	v_mfma_f32_16x16x32_bf16 v[110:113], v[196:199], v[236:239], v[110:113]
	v_mfma_f32_16x16x32_bf16 v[98:101], v[168:171], v[244:247], v[98:101]
	v_mfma_f32_16x16x32_bf16 v[102:105], v[196:199], v[244:247], v[102:105]
	s_setprio 0
	s_setprio 1
	v_mfma_f32_16x16x32_bf16 v[90:93], v[200:203], v[216:219], v[90:93]
	v_mfma_f32_16x16x32_bf16 v[94:97], v[208:211], v[216:219], v[94:97]
	v_mfma_f32_16x16x32_bf16 v[82:85], v[200:203], v[224:227], v[82:85]
	v_mfma_f32_16x16x32_bf16 v[86:89], v[208:211], v[224:227], v[86:89]
	v_mfma_f32_16x16x32_bf16 v[74:77], v[200:203], v[232:235], v[74:77]
	v_mfma_f32_16x16x32_bf16 v[78:81], v[208:211], v[232:235], v[78:81]
	v_mfma_f32_16x16x32_bf16 v[66:69], v[200:203], v[240:243], v[66:69]
	v_mfma_f32_16x16x32_bf16 v[70:73], v[208:211], v[240:243], v[70:73]
	v_mfma_f32_16x16x32_bf16 v[90:93], v[204:207], v[220:223], v[90:93]
	v_mfma_f32_16x16x32_bf16 v[94:97], v[212:215], v[220:223], v[94:97]
	v_mfma_f32_16x16x32_bf16 v[82:85], v[204:207], v[228:231], v[82:85]
	v_mfma_f32_16x16x32_bf16 v[86:89], v[212:215], v[228:231], v[86:89]
	v_mfma_f32_16x16x32_bf16 v[74:77], v[204:207], v[236:239], v[74:77]
	v_mfma_f32_16x16x32_bf16 v[78:81], v[212:215], v[236:239], v[78:81]
	v_mfma_f32_16x16x32_bf16 v[66:69], v[204:207], v[244:247], v[66:69]
	v_mfma_f32_16x16x32_bf16 v[70:73], v[212:215], v[244:247], v[70:73]
	s_setprio 0
	s_barrier
; #define PG8_STAGE(bufoff, gbase) do { _Pragma("unroll") for (int _i = 0; _i < 2; ++_i) \
;     __builtin_amdgcn_global_load_lds((const unsigned*)((const char*)(gbase) + voff[_i]), (LAS unsigned*)(lds + (bufoff) + ldsw + _i * 8192), 16, 0, 0); } while (0)
; #define PG8_LDA(dst, b, h) do { _Pragma("unroll") for (int m = 0; m < 4; ++m) _Pragma("unroll") for (int k = 0; k < 2; ++k) dst[m][k] = *(const LAS bf16x8*)(lds + PG8_SA(b, h) + aoff + m * 2048 + k * 1024); } while (0)
; #define PG8_LDB(dst, b, h) do { _Pragma("unroll") for (int n = 0; n < 2; ++n) _Pragma("unroll") for (int k = 0; k < 2; ++k) dst[n][k] = *(const LAS bf16x8*)(lds + PG8_SB(b, h) + boff + n * 2048 + k * 1024); } while (0)
; #define PG8_WAIT_V(n) asm volatile("s_waitcnt vmcnt(" #n ")" ::: "memory")
; #define PG8_WAIT_L(n) asm volatile("s_waitcnt lgkmcnt(" #n ")" ::: "memory")
; #define PG8_BAR __builtin_amdgcn_s_barrier()
; #define PG8_SCHED __builtin_amdgcn_sched_barrier(0)
; template <int EPI, bool ALIGN_EPI = true, bool SP2 = true>
; DI void gemm8_phase(const GemmArgs& g, char* lds_) {
;     ...
;         PG8_LDA(At, 0, 1); PG8_STAGE(PG8_SB(0, 0), b2); PG8_STAGE(PG8_SB(0, 1), b2 + hstep); PG8_STAGE(PG8_SA(0, 0), a2);
;         if (relax) PG8_WAIT_V(24); else PG8_WAIT_V(8);
;         PG8_WAIT_L(0); PG8_BAR; PG8_MMA(1, 0, At, B0); PG8_MMA(1, 1, At, B1); PG8_BAR; PG8_SCHED;
;         PG8_LDB(B0, 1, 0); PG8_LDB(B1, 1, 1); PG8_SCHED; PG8_LDA(At, 1, 0); PG8_STAGE(PG8_SA(0, 1), a2 + hstep);
;         PG8_WAIT_V(8); PG8_WAIT_L(0); PG8_BAR; PG8_MMA(0, 0, At, B0); PG8_MMA(0, 1, At, B1); PG8_BAR; PG8_SCHED;
	s_mov_b32 m0, s9
	s_add_u32 s24, s86, 0x40000
	ds_read_b128 v[216:219], v139 offset:16384
	ds_read_b128 v[220:223], v139 offset:17408
	ds_read_b128 v[224:227], v139 offset:18432
	ds_read_b128 v[228:231], v139 offset:19456
	ds_read_b128 v[232:235], v139 offset:20480
	ds_read_b128 v[236:239], v139 offset:21504
	ds_read_b128 v[240:243], v139 offset:22528
	ds_read_b128 v[244:247], v139 offset:23552
	global_load_lds_dwordx4 v0, s[86:87]
	s_mov_b32 m0, s10
	s_addc_u32 s25, s87, 0
	global_load_lds_dwordx4 v130, s[86:87]
	s_mov_b32 m0, s11
	s_nop 0
	global_load_lds_dwordx4 v0, s[24:25]
	s_mov_b32 m0, s28
	s_nop 0
	global_load_lds_dwordx4 v130, s[24:25]
	s_mov_b32 m0, s18
	s_nop 0
	global_load_lds_dwordx4 v0, s[90:91]
	s_mov_b32 m0, s50
	s_nop 0
	global_load_lds_dwordx4 v130, s[90:91]
	s_waitcnt vmcnt(8)
	s_waitcnt lgkmcnt(0)
	s_barrier
	s_setprio 1
	s_waitcnt lgkmcnt(0)
	v_mfma_f32_16x16x32_bf16 v[58:61], v[158:161], v[216:219], v[58:61]
	v_mfma_f32_16x16x32_bf16 v[62:65], v[192:195], v[216:219], v[62:65]
	v_mfma_f32_16x16x32_bf16 v[50:53], v[158:161], v[224:227], v[50:53]
	v_mfma_f32_16x16x32_bf16 v[54:57], v[192:195], v[224:227], v[54:57]
	v_mfma_f32_16x16x32_bf16 v[42:45], v[158:161], v[232:235], v[42:45]
	v_mfma_f32_16x16x32_bf16 v[46:49], v[192:195], v[232:235], v[46:49]
	v_mfma_f32_16x16x32_bf16 v[34:37], v[158:161], v[240:243], v[34:37]
	v_mfma_f32_16x16x32_bf16 v[38:41], v[192:195], v[240:243], v[38:41]
	v_mfma_f32_16x16x32_bf16 v[58:61], v[168:171], v[220:223], v[58:61]
	v_mfma_f32_16x16x32_bf16 v[62:65], v[196:199], v[220:223], v[62:65]
	v_mfma_f32_16x16x32_bf16 v[50:53], v[168:171], v[228:231], v[50:53]
	v_mfma_f32_16x16x32_bf16 v[54:57], v[196:199], v[228:231], v[54:57]
	v_mfma_f32_16x16x32_bf16 v[42:45], v[168:171], v[236:239], v[42:45]
	v_mfma_f32_16x16x32_bf16 v[46:49], v[196:199], v[236:239], v[46:49]
	v_mfma_f32_16x16x32_bf16 v[34:37], v[168:171], v[244:247], v[34:37]
	v_mfma_f32_16x16x32_bf16 v[38:41], v[196:199], v[244:247], v[38:41]
	s_setprio 0
	s_setprio 1
	v_mfma_f32_16x16x32_bf16 v[26:29], v[200:203], v[216:219], v[26:29]
	v_mfma_f32_16x16x32_bf16 v[30:33], v[208:211], v[216:219], v[30:33]
	v_mfma_f32_16x16x32_bf16 v[18:21], v[200:203], v[224:227], v[18:21]
	v_mfma_f32_16x16x32_bf16 v[22:25], v[208:211], v[224:227], v[22:25]
	v_mfma_f32_16x16x32_bf16 v[10:13], v[200:203], v[232:235], v[10:13]
	v_mfma_f32_16x16x32_bf16 v[14:17], v[208:211], v[232:235], v[14:17]
	v_mfma_f32_16x16x32_bf16 v[2:5], v[200:203], v[240:243], v[2:5]
	v_mfma_f32_16x16x32_bf16 v[6:9], v[208:211], v[240:243], v[6:9]
	v_mfma_f32_16x16x32_bf16 v[26:29], v[204:207], v[220:223], v[26:29]
	v_mfma_f32_16x16x32_bf16 v[30:33], v[212:215], v[220:223], v[30:33]
	v_mfma_f32_16x16x32_bf16 v[18:21], v[204:207], v[228:231], v[18:21]
	v_mfma_f32_16x16x32_bf16 v[22:25], v[212:215], v[228:231], v[22:25]
	v_mfma_f32_16x16x32_bf16 v[10:13], v[204:207], v[236:239], v[10:13]
	v_mfma_f32_16x16x32_bf16 v[14:17], v[212:215], v[236:239], v[14:17]
	v_mfma_f32_16x16x32_bf16 v[2:5], v[204:207], v[244:247], v[2:5]
	v_mfma_f32_16x16x32_bf16 v[6:9], v[212:215], v[244:247], v[6:9]
	s_setprio 0
	s_barrier
	ds_read_b128 v[158:161], v149
	ds_read_b128 v[168:171], v150
	ds_read_b128 v[192:195], v151
	ds_read_b128 v[196:199], v152
	ds_read_b128 v[200:203], v153
	ds_read_b128 v[204:207], v154
	ds_read_b128 v[208:211], v155
	ds_read_b128 v[212:215], v156
	s_add_u32 s24, s90, 0x40000
	s_addc_u32 s25, s91, 0
	s_mov_b32 m0, s51
	ds_read_b128 v[216:219], v139 offset:32768
	ds_read_b128 v[220:223], v139 offset:33792
	ds_read_b128 v[224:227], v139 offset:34816
	ds_read_b128 v[228:231], v139 offset:35840
	ds_read_b128 v[232:235], v139 offset:36864
	ds_read_b128 v[236:239], v139 offset:37888
	ds_read_b128 v[240:243], v139 offset:38912
	ds_read_b128 v[244:247], v139 offset:39936
	global_load_lds_dwordx4 v0, s[24:25]
	s_mov_b32 m0, s57
	s_nop 0
	global_load_lds_dwordx4 v130, s[24:25]
	s_waitcnt vmcnt(8)
	s_waitcnt lgkmcnt(0)
	s_barrier
; #define PG8_STAGE(bufoff, gbase) do { _Pragma("unroll") for (int _i = 0; _i < 2; ++_i) \
;     __builtin_amdgcn_global_load_lds((const unsigned*)((const char*)(gbase) + voff[_i]), (LAS unsigned*)(lds + (bufoff) + ldsw + _i * 8192), 16, 0, 0); } while (0)
; #define PG8_LDA(dst, b, h) do { _Pragma("unroll") for (int m = 0; m < 4; ++m) _Pragma("unroll") for (int k = 0; k < 2; ++k) dst[m][k] = *(const LAS bf16x8*)(lds + PG8_SA(b, h) + aoff + m * 2048 + k * 1024); } while (0)
; #define PG8_WAIT_V(n) asm volatile("s_waitcnt vmcnt(" #n ")" ::: "memory")
; #define PG8_WAIT_L(n) asm volatile("s_waitcnt lgkmcnt(" #n ")" ::: "memory")
; #define PG8_BAR __builtin_amdgcn_s_barrier()
; #define PG8_SCHED __builtin_amdgcn_sched_barrier(0)
; template <int EPI, bool ALIGN_EPI = true, bool SP2 = true>
; DI void gemm8_phase(const GemmArgs& g, char* lds_) {
;     ...
; #pragma unroll 1
;     for (int t = 0; t < nt; t += 2) {
;     ...
;         PG8_WAIT_V(8); PG8_WAIT_L(0); PG8_BAR; PG8_MMA(0, 0, At, B0); PG8_MMA(0, 1, At, B1); PG8_BAR; PG8_SCHED;
;         PG8_LDA(At, 1, 1); PG8_STAGE(PG8_SB(1, 0), b3); PG8_STAGE(PG8_SB(1, 1), b3 + hstep); PG8_STAGE(PG8_SA(1, 0), a3);
;         PG8_WAIT_V(8); PG8_WAIT_L(0); PG8_BAR; PG8_MMA(1, 0, At, B0); PG8_MMA(1, 1, At, B1); PG8_BAR; PG8_SCHED;
	s_setprio 1
	s_waitcnt lgkmcnt(0)
	v_mfma_f32_16x16x32_bf16 v[122:125], v[158:161], v[216:219], v[122:125]
	v_mfma_f32_16x16x32_bf16 v[126:129], v[192:195], v[216:219], v[126:129]
	v_mfma_f32_16x16x32_bf16 v[114:117], v[158:161], v[224:227], v[114:117]
	v_mfma_f32_16x16x32_bf16 v[118:121], v[192:195], v[224:227], v[118:121]
	v_mfma_f32_16x16x32_bf16 v[106:109], v[158:161], v[232:235], v[106:109]
	v_mfma_f32_16x16x32_bf16 v[110:113], v[192:195], v[232:235], v[110:113]
	v_mfma_f32_16x16x32_bf16 v[98:101], v[158:161], v[240:243], v[98:101]
	v_mfma_f32_16x16x32_bf16 v[102:105], v[192:195], v[240:243], v[102:105]
	v_mfma_f32_16x16x32_bf16 v[122:125], v[168:171], v[220:223], v[122:125]
	v_mfma_f32_16x16x32_bf16 v[126:129], v[196:199], v[220:223], v[126:129]
	v_mfma_f32_16x16x32_bf16 v[114:117], v[168:171], v[228:231], v[114:117]
	v_mfma_f32_16x16x32_bf16 v[118:121], v[196:199], v[228:231], v[118:121]
	v_mfma_f32_16x16x32_bf16 v[106:109], v[168:171], v[236:239], v[106:109]
	v_mfma_f32_16x16x32_bf16 v[110:113], v[196:199], v[236:239], v[110:113]
	v_mfma_f32_16x16x32_bf16 v[98:101], v[168:171], v[244:247], v[98:101]
	v_mfma_f32_16x16x32_bf16 v[102:105], v[196:199], v[244:247], v[102:105]
	s_setprio 0
	s_setprio 1
	v_mfma_f32_16x16x32_bf16 v[90:93], v[200:203], v[216:219], v[90:93]
	v_mfma_f32_16x16x32_bf16 v[94:97], v[208:211], v[216:219], v[94:97]
	v_mfma_f32_16x16x32_bf16 v[82:85], v[200:203], v[224:227], v[82:85]
	v_mfma_f32_16x16x32_bf16 v[86:89], v[208:211], v[224:227], v[86:89]
	v_mfma_f32_16x16x32_bf16 v[74:77], v[200:203], v[232:235], v[74:77]
	v_mfma_f32_16x16x32_bf16 v[78:81], v[208:211], v[232:235], v[78:81]
	v_mfma_f32_16x16x32_bf16 v[66:69], v[200:203], v[240:243], v[66:69]
	v_mfma_f32_16x16x32_bf16 v[70:73], v[208:211], v[240:243], v[70:73]
	v_mfma_f32_16x16x32_bf16 v[90:93], v[204:207], v[220:223], v[90:93]
	v_mfma_f32_16x16x32_bf16 v[94:97], v[212:215], v[220:223], v[94:97]
	v_mfma_f32_16x16x32_bf16 v[82:85], v[204:207], v[228:231], v[82:85]
	v_mfma_f32_16x16x32_bf16 v[86:89], v[212:215], v[228:231], v[86:89]
	v_mfma_f32_16x16x32_bf16 v[74:77], v[204:207], v[236:239], v[74:77]
	v_mfma_f32_16x16x32_bf16 v[78:81], v[212:215], v[236:239], v[78:81]
	v_mfma_f32_16x16x32_bf16 v[66:69], v[204:207], v[244:247], v[66:69]
	v_mfma_f32_16x16x32_bf16 v[70:73], v[212:215], v[244:247], v[70:73]
	s_setprio 0
	s_barrier
	s_mov_b32 m0, s69
	s_add_u32 s24, s86, 0x40080
	ds_read_b128 v[216:219], v139 offset:49152
	ds_read_b128 v[220:223], v139 offset:50176
	ds_read_b128 v[224:227], v139 offset:51200
	ds_read_b128 v[228:231], v139 offset:52224
	ds_read_b128 v[232:235], v139 offset:53248
	ds_read_b128 v[236:239], v139 offset:54272
	ds_read_b128 v[240:243], v139 offset:55296
	ds_read_b128 v[244:247], v139 offset:56320
	global_load_lds_dwordx4 v164, s[86:87]
	s_mov_b32 m0, s8
	s_addc_u32 s25, s87, 0
	global_load_lds_dwordx4 v165, s[86:87]
	s_mov_b32 m0, s15
	s_nop 0
	global_load_lds_dwordx4 v0, s[24:25]
	s_mov_b32 m0, s14
	s_nop 0
	global_load_lds_dwordx4 v130, s[24:25]
	s_mov_b32 m0, s13
	s_nop 0
	global_load_lds_dwordx4 v164, s[90:91]
	s_mov_b32 m0, s12
	s_nop 0
	global_load_lds_dwordx4 v165, s[90:91]
	s_waitcnt vmcnt(8)
	s_waitcnt lgkmcnt(0)
	s_barrier
	s_setprio 1
	s_waitcnt lgkmcnt(0)
	v_mfma_f32_16x16x32_bf16 v[58:61], v[158:161], v[216:219], v[58:61]
	v_mfma_f32_16x16x32_bf16 v[62:65], v[192:195], v[216:219], v[62:65]
	v_mfma_f32_16x16x32_bf16 v[50:53], v[158:161], v[224:227], v[50:53]
	v_mfma_f32_16x16x32_bf16 v[54:57], v[192:195], v[224:227], v[54:57]
	v_mfma_f32_16x16x32_bf16 v[42:45], v[158:161], v[232:235], v[42:45]
	v_mfma_f32_16x16x32_bf16 v[46:49], v[192:195], v[232:235], v[46:49]
	v_mfma_f32_16x16x32_bf16 v[34:37], v[158:161], v[240:243], v[34:37]
	v_mfma_f32_16x16x32_bf16 v[38:41], v[192:195], v[240:243], v[38:41]
	v_mfma_f32_16x16x32_bf16 v[58:61], v[168:171], v[220:223], v[58:61]
	v_mfma_f32_16x16x32_bf16 v[62:65], v[196:199], v[220:223], v[62:65]
	v_mfma_f32_16x16x32_bf16 v[50:53], v[168:171], v[228:231], v[50:53]
	v_mfma_f32_16x16x32_bf16 v[54:57], v[196:199], v[228:231], v[54:57]
	v_mfma_f32_16x16x32_bf16 v[42:45], v[168:171], v[236:239], v[42:45]
	v_mfma_f32_16x16x32_bf16 v[46:49], v[196:199], v[236:239], v[46:49]
	v_mfma_f32_16x16x32_bf16 v[34:37], v[168:171], v[244:247], v[34:37]
	v_mfma_f32_16x16x32_bf16 v[38:41], v[196:199], v[244:247], v[38:41]
	s_setprio 0
	s_setprio 1
	v_mfma_f32_16x16x32_bf16 v[26:29], v[200:203], v[216:219], v[26:29]
	v_mfma_f32_16x16x32_bf16 v[30:33], v[208:211], v[216:219], v[30:33]
	v_mfma_f32_16x16x32_bf16 v[18:21], v[200:203], v[224:227], v[18:21]
	v_mfma_f32_16x16x32_bf16 v[22:25], v[208:211], v[224:227], v[22:25]
	v_mfma_f32_16x16x32_bf16 v[10:13], v[200:203], v[232:235], v[10:13]
	v_mfma_f32_16x16x32_bf16 v[14:17], v[208:211], v[232:235], v[14:17]
	v_mfma_f32_16x16x32_bf16 v[2:5], v[200:203], v[240:243], v[2:5]
	v_mfma_f32_16x16x32_bf16 v[6:9], v[208:211], v[240:243], v[6:9]
	v_mfma_f32_16x16x32_bf16 v[26:29], v[204:207], v[220:223], v[26:29]
	v_mfma_f32_16x16x32_bf16 v[30:33], v[212:215], v[220:223], v[30:33]
	v_mfma_f32_16x16x32_bf16 v[18:21], v[204:207], v[228:231], v[18:21]
	v_mfma_f32_16x16x32_bf16 v[22:25], v[212:215], v[228:231], v[22:25]
	v_mfma_f32_16x16x32_bf16 v[10:13], v[204:207], v[236:239], v[10:13]
	v_mfma_f32_16x16x32_bf16 v[14:17], v[212:215], v[236:239], v[14:17]
	v_mfma_f32_16x16x32_bf16 v[2:5], v[204:207], v[244:247], v[2:5]
	v_mfma_f32_16x16x32_bf16 v[6:9], v[212:215], v[244:247], v[6:9]
	s_setprio 0
	s_barrier
	s_add_i32 vcc_lo, vcc_lo, 2
	s_add_u32 s41, s41, 0x100
	s_addc_u32 s43, s43, 0
	s_cmp_gt_u32 vcc_lo, 13
	s_mov_b64 s[34:35], s[84:85]
	s_cbranch_scc0 .LBB0_292
	s_and_b64 vcc, exec, s[38:39]
	s_cbranch_vccz .LBB0_295
	s_barrier

; #define PG8_WAIT_V(n) asm volatile("s_waitcnt vmcnt(" #n ")" ::: "memory")
; #define PG8_BAR __builtin_amdgcn_s_barrier()
; template <int EPI, bool ALIGN_EPI = true, bool SP2 = true>
; DI void gemm8_phase(const GemmArgs& g, char* lds_) {
;     ...
;   f32x4 acc[2][2][4][2];
; #pragma unroll
;   for (int a = 0; a < 2; ++a)
; #pragma unroll
;     for (int b = 0; b < 2; ++b)
; #pragma unroll
;       for (int m = 0; m < 4; ++m)
; #pragma unroll
;         for (int n = 0; n < 2; ++n) acc[a][b][m][n] = f32x4{0.f, 0.f, 0.f, 0.f};
;   bf16x8 At[4][2], B0[2][2], B1[2][2];
;   const char* cA = (const char*)g.A0 + (size_t)cpm * tstep;
;   const char* cB = (const char*)g.Bt0 + (size_t)cpn * tstep;
;   PG8_WAIT_V(0);
;   __syncthreads();
;   if constexpr (SP2) {
;     PG8_STAGE(PG8_SB(0, 0), cB); PG8_STAGE(PG8_SB(0, 1), cB + hstep); PG8_STAGE(PG8_SA(0, 0), cA); PG8_STAGE(PG8_SA(0, 1), cA + hstep);
;     if (wr == 1) PG8_BAR;
;     PG8_WAIT_V(2); PG8_BAR;
;     PG8_STAGE(PG8_SB(1, 0), cB + kstep); PG8_STAGE(PG8_SA(1, 0), cA + kstep); PG8_STAGE(PG8_SB(1, 1), cB + hstep + kstep);
;     PG8_WAIT_V(6); PG8_BAR;
;   } else {
;     PG8_STAGE(PG8_SB(0, 0), cB); PG8_STAGE(PG8_SA(0, 0), cA); PG8_STAGE(PG8_SB(0, 1), cB + hstep); PG8_STAGE(PG8_SA(0, 1), cA + hstep);
;     if (wr == 1) PG8_BAR;
;     PG8_WAIT_V(4); PG8_BAR;
;     PG8_STAGE(PG8_SB(1, 0), cB + kstep); PG8_STAGE(PG8_SA(1, 0), cA + kstep); PG8_STAGE(PG8_SB(1, 1), cB + hstep + kstep);
;     PG8_WAIT_V(6); PG8_BAR;
;   }
;   for (;;) {
;     const int nid = (int)blockIdx.x + (ui + 1) * G;
;     const bool has_next = nid < total;
;     if (has_next) tile_map(nid, g.NTm, g.NTn, npm, npn, g.gm);
;     const char* nA = has_next ? (const char*)g.A0 + (size_t)npm * tstep : cA;
;     const char* nB = has_next ? (const char*)g.Bt0 + (size_t)npn * tstep : cB;
; #pragma unroll 1
;     for (int t = 0; t < nt; t += 2) {
;       const bool last = (t == nt - 2);
;       const char* a1 = cA + (size_t)(t + 1) * kstep;
;       const char* a2 = last ? nA : cA + (size_t)(t + 2) * kstep;
;       const char* b2 = last ? nB : cB + (size_t)(t + 2) * kstep;
;       const char* a3 = a2 + kstep; const char* b3 = b2 + kstep;
;       if constexpr (SP2) {
;         const bool relax = EPI_VM > 0 && t == 0 && ui > 0;
;         PG8_LDB(B0, 0, 0); PG8_LDB(B1, 0, 1); PG8_SCHED; PG8_LDA(At, 0, 0); PG8_STAGE(PG8_SA(1, 1), a1 + hstep);
.LBB0_380:
	s_ashr_i32 s45, s44, 31
	s_lshl_b64 s[24:25], s[44:45], 19
	s_add_u32 s84, s7, s24
	s_addc_u32 s85, s8, s25
	s_and_b64 s[24:25], s[62:63], exec
	s_cselect_b32 s45, s85, s41
	s_cselect_b32 s47, s84, s40
	s_add_u32 s50, s40, 0x100
	v_mov_b32_e32 v2, 0
	s_addc_u32 s51, s41, 0
	s_mov_b32 vcc_lo, -2
	v_mov_b32_e32 v3, v2
	v_mov_b32_e32 v4, v2
	v_mov_b32_e32 v5, v2
	v_mov_b32_e32 v6, v2
	v_mov_b32_e32 v7, v2
	v_mov_b32_e32 v8, v2
	v_mov_b32_e32 v9, v2
	v_mov_b32_e32 v10, v2
	v_mov_b32_e32 v11, v2
	v_mov_b32_e32 v12, v2
	v_mov_b32_e32 v13, v2
	v_mov_b32_e32 v14, v2
	v_mov_b32_e32 v15, v2
	v_mov_b32_e32 v16, v2
	v_mov_b32_e32 v17, v2
	v_mov_b32_e32 v18, v2
	v_mov_b32_e32 v19, v2
	v_mov_b32_e32 v20, v2
	v_mov_b32_e32 v21, v2
	v_mov_b32_e32 v22, v2
	v_mov_b32_e32 v23, v2
	v_mov_b32_e32 v24, v2
	v_mov_b32_e32 v25, v2
	v_mov_b32_e32 v26, v2
	v_mov_b32_e32 v27, v2
	v_mov_b32_e32 v28, v2
	v_mov_b32_e32 v29, v2
	v_mov_b32_e32 v30, v2
	v_mov_b32_e32 v31, v2
	v_mov_b32_e32 v32, v2
	v_mov_b32_e32 v33, v2
	v_mov_b32_e32 v34, v2
	v_mov_b32_e32 v35, v2
	v_mov_b32_e32 v36, v2
	v_mov_b32_e32 v37, v2
	v_mov_b32_e32 v38, v2
	v_mov_b32_e32 v39, v2
	v_mov_b32_e32 v40, v2
	v_mov_b32_e32 v41, v2
	v_mov_b32_e32 v42, v2
	v_mov_b32_e32 v43, v2
	v_mov_b32_e32 v44, v2
	v_mov_b32_e32 v45, v2
	v_mov_b32_e32 v46, v2
	v_mov_b32_e32 v47, v2
	v_mov_b32_e32 v48, v2
	v_mov_b32_e32 v49, v2
	v_mov_b32_e32 v50, v2
	v_mov_b32_e32 v51, v2
	v_mov_b32_e32 v52, v2
	v_mov_b32_e32 v53, v2
	v_mov_b32_e32 v54, v2
	v_mov_b32_e32 v55, v2
	v_mov_b32_e32 v56, v2
	v_mov_b32_e32 v57, v2
	v_mov_b32_e32 v58, v2
	v_mov_b32_e32 v59, v2
	v_mov_b32_e32 v60, v2
	v_mov_b32_e32 v61, v2
	v_mov_b32_e32 v62, v2
	v_mov_b32_e32 v63, v2
	v_mov_b32_e32 v64, v2
	v_mov_b32_e32 v65, v2
	v_mov_b32_e32 v66, v2
	v_mov_b32_e32 v67, v2
	v_mov_b32_e32 v68, v2
	v_mov_b32_e32 v69, v2
	v_mov_b32_e32 v70, v2
	v_mov_b32_e32 v71, v2
	v_mov_b32_e32 v72, v2
	v_mov_b32_e32 v73, v2
	v_mov_b32_e32 v74, v2
	v_mov_b32_e32 v75, v2
	v_mov_b32_e32 v76, v2
	v_mov_b32_e32 v77, v2
	v_mov_b32_e32 v78, v2
	v_mov_b32_e32 v79, v2
	v_mov_b32_e32 v80, v2
	v_mov_b32_e32 v81, v2
	v_mov_b32_e32 v82, v2
	v_mov_b32_e32 v83, v2
	v_mov_b32_e32 v84, v2
	v_mov_b32_e32 v85, v2
	v_mov_b32_e32 v86, v2
	v_mov_b32_e32 v87, v2
	v_mov_b32_e32 v88, v2
	v_mov_b32_e32 v89, v2
	v_mov_b32_e32 v90, v2
	v_mov_b32_e32 v91, v2
	v_mov_b32_e32 v92, v2
	v_mov_b32_e32 v93, v2
	v_mov_b32_e32 v94, v2
	v_mov_b32_e32 v95, v2
	v_mov_b32_e32 v96, v2
	v_mov_b32_e32 v97, v2
	v_mov_b32_e32 v98, v2
	v_mov_b32_e32 v99, v2
	v_mov_b32_e32 v100, v2
	v_mov_b32_e32 v101, v2
	v_mov_b32_e32 v102, v2
	v_mov_b32_e32 v103, v2
	v_mov_b32_e32 v104, v2
	v_mov_b32_e32 v105, v2
	v_mov_b32_e32 v106, v2
	v_mov_b32_e32 v107, v2
	v_mov_b32_e32 v108, v2
	v_mov_b32_e32 v109, v2
	v_mov_b32_e32 v110, v2
	v_mov_b32_e32 v111, v2
	v_mov_b32_e32 v112, v2
	v_mov_b32_e32 v113, v2
	v_mov_b32_e32 v114, v2
	v_mov_b32_e32 v115, v2
	v_mov_b32_e32 v116, v2
	v_mov_b32_e32 v117, v2
	v_mov_b32_e32 v118, v2
	v_mov_b32_e32 v119, v2
	v_mov_b32_e32 v120, v2
	v_mov_b32_e32 v121, v2
	v_mov_b32_e32 v122, v2
	v_mov_b32_e32 v123, v2
	v_mov_b32_e32 v124, v2
	v_mov_b32_e32 v125, v2
	v_mov_b32_e32 v126, v2
	v_mov_b32_e32 v127, v2
	v_mov_b32_e32 v128, v2
	v_mov_b32_e32 v129, v2
	v_add_u32_e32 v164, 0x80, v130
	v_add_u32_e32 v165, 0x80, v132
.LBB0_381:
	v_or_b32_e32 v0, 0x10000, v149
	v_add_u32_e32 v142, 0x10400, v149
	ds_read_b128 v[138:141], v0
	ds_read_b128 v[142:145], v142
	v_add_u32_e32 v0, 0x10800, v149
	v_add_u32_e32 v146, 0x10c00, v149
	ds_read_b128 v[154:157], v0
	ds_read_b128 v[158:161], v146
	v_or_b32_e32 v0, 0x14000, v149
	v_add_u32_e32 v146, 0x14400, v149
	ds_read_b128 v[168:171], v0
	ds_read_b128 v[192:195], v146
	v_add_u32_e32 v0, 0x14800, v149
	v_add_u32_e32 v146, 0x14c00, v149
	ds_read_b128 v[196:199], v0
	ds_read_b128 v[200:203], v146
	s_add_u32 s40, s34, 0x100
	s_addc_u32 s41, s35, 0
	s_cmp_eq_u32 vcc_lo, 12
	s_cselect_b32 s91, s49, s41
	s_cselect_b32 s90, s48, s40
	s_cselect_b32 s87, s45, s51
	s_cselect_b32 s86, s47, s50
	s_add_i32 m0, s9, 0xc000
	ds_read_b128 v[204:207], v150
	ds_read_b128 v[208:211], v150 offset:1024
	ds_read_b128 v[212:215], v150 offset:2048
	ds_read_b128 v[216:219], v150 offset:3072
	ds_read_b128 v[220:223], v150 offset:4096
	ds_read_b128 v[224:227], v150 offset:5120
	ds_read_b128 v[228:231], v150 offset:6144
	ds_read_b128 v[232:235], v150 offset:7168
	global_load_lds_dwordx4 v134, s[34:35]
	s_add_i32 m0, s9, 0xe000
	s_nop 0
	global_load_lds_dwordx4 v136, s[34:35]
	s_waitcnt vmcnt(8)
	s_waitcnt lgkmcnt(0)
	s_barrier
; #define PG8_STAGE(bufoff, gbase) do { _Pragma("unroll") for (int _i = 0; _i < 2; ++_i) \
;     __builtin_amdgcn_global_load_lds((const unsigned*)((const char*)(gbase) + voff[_i]), (LAS unsigned*)(lds + (bufoff) + ldsw + _i * 8192), 16, 0, 0); } while (0)
; #define PG8_LDA(dst, b, h) do { _Pragma("unroll") for (int m = 0; m < 4; ++m) _Pragma("unroll") for (int k = 0; k < 2; ++k) dst[m][k] = *(const LAS bf16x8*)(lds + PG8_SA(b, h) + aoff + m * 2048 + k * 1024); } while (0)
; #define PG8_WAIT_V(n) asm volatile("s_waitcnt vmcnt(" #n ")" ::: "memory")
; #define PG8_WAIT_L(n) asm volatile("s_waitcnt lgkmcnt(" #n ")" ::: "memory")
; #define PG8_BAR __builtin_amdgcn_s_barrier()
; #define PG8_SCHED __builtin_amdgcn_sched_barrier(0)
; template <int EPI, bool ALIGN_EPI = true, bool SP2 = true>
; DI void gemm8_phase(const GemmArgs& g, char* lds_) {
;     ...
;         PG8_WAIT_L(0); PG8_BAR; PG8_MMA(0, 0, At, B0); PG8_MMA(0, 1, At, B1); PG8_BAR; PG8_SCHED;
;         PG8_LDA(At, 0, 1); PG8_STAGE(PG8_SB(0, 0), b2); PG8_STAGE(PG8_SB(0, 1), b2 + hstep); PG8_STAGE(PG8_SA(0, 0), a2);
;         if (relax) PG8_WAIT_V(24); else PG8_WAIT_V(8);
;         PG8_WAIT_L(0); PG8_BAR; PG8_MMA(1, 0, At, B0); PG8_MMA(1, 1, At, B1); PG8_BAR; PG8_SCHED;
	s_setprio 1
	s_waitcnt lgkmcnt(0)
	v_mfma_f32_16x16x32_bf16 v[126:129], v[138:141], v[204:207], v[126:129]
	v_mfma_f32_16x16x32_bf16 v[122:125], v[154:157], v[204:207], v[122:125]
	v_mfma_f32_16x16x32_bf16 v[118:121], v[138:141], v[212:215], v[118:121]
	v_mfma_f32_16x16x32_bf16 v[114:117], v[154:157], v[212:215], v[114:117]
	v_mfma_f32_16x16x32_bf16 v[110:113], v[138:141], v[220:223], v[110:113]
	v_mfma_f32_16x16x32_bf16 v[106:109], v[154:157], v[220:223], v[106:109]
	v_mfma_f32_16x16x32_bf16 v[102:105], v[138:141], v[228:231], v[102:105]
	v_mfma_f32_16x16x32_bf16 v[98:101], v[154:157], v[228:231], v[98:101]
	v_mfma_f32_16x16x32_bf16 v[126:129], v[142:145], v[208:211], v[126:129]
	v_mfma_f32_16x16x32_bf16 v[122:125], v[158:161], v[208:211], v[122:125]
	v_mfma_f32_16x16x32_bf16 v[118:121], v[142:145], v[216:219], v[118:121]
	v_mfma_f32_16x16x32_bf16 v[114:117], v[158:161], v[216:219], v[114:117]
	v_mfma_f32_16x16x32_bf16 v[110:113], v[142:145], v[224:227], v[110:113]
	v_mfma_f32_16x16x32_bf16 v[106:109], v[158:161], v[224:227], v[106:109]
	v_mfma_f32_16x16x32_bf16 v[102:105], v[142:145], v[232:235], v[102:105]
	v_mfma_f32_16x16x32_bf16 v[98:101], v[158:161], v[232:235], v[98:101]
	s_setprio 0
	s_setprio 1
	v_mfma_f32_16x16x32_bf16 v[94:97], v[168:171], v[204:207], v[94:97]
	v_mfma_f32_16x16x32_bf16 v[90:93], v[196:199], v[204:207], v[90:93]
	v_mfma_f32_16x16x32_bf16 v[86:89], v[168:171], v[212:215], v[86:89]
	v_mfma_f32_16x16x32_bf16 v[82:85], v[196:199], v[212:215], v[82:85]
	v_mfma_f32_16x16x32_bf16 v[78:81], v[168:171], v[220:223], v[78:81]
	v_mfma_f32_16x16x32_bf16 v[74:77], v[196:199], v[220:223], v[74:77]
	v_mfma_f32_16x16x32_bf16 v[70:73], v[168:171], v[228:231], v[70:73]
	v_mfma_f32_16x16x32_bf16 v[66:69], v[196:199], v[228:231], v[66:69]
	v_mfma_f32_16x16x32_bf16 v[94:97], v[192:195], v[208:211], v[94:97]
	v_mfma_f32_16x16x32_bf16 v[90:93], v[200:203], v[208:211], v[90:93]
	v_mfma_f32_16x16x32_bf16 v[86:89], v[192:195], v[216:219], v[86:89]
	v_mfma_f32_16x16x32_bf16 v[82:85], v[200:203], v[216:219], v[82:85]
	v_mfma_f32_16x16x32_bf16 v[78:81], v[192:195], v[224:227], v[78:81]
	v_mfma_f32_16x16x32_bf16 v[74:77], v[200:203], v[224:227], v[74:77]
	v_mfma_f32_16x16x32_bf16 v[70:73], v[192:195], v[232:235], v[70:73]
	v_mfma_f32_16x16x32_bf16 v[66:69], v[200:203], v[232:235], v[66:69]
	s_setprio 0
	s_barrier
	s_mov_b32 m0, s10
	s_add_u32 s24, s86, 0x40000
	ds_read_b128 v[204:207], v150 offset:16384
	ds_read_b128 v[208:211], v150 offset:17408
	ds_read_b128 v[212:215], v150 offset:18432
	ds_read_b128 v[216:219], v150 offset:19456
	ds_read_b128 v[220:223], v150 offset:20480
	ds_read_b128 v[224:227], v150 offset:21504
	ds_read_b128 v[228:231], v150 offset:22528
	ds_read_b128 v[232:235], v150 offset:23552
	global_load_lds_dwordx4 v130, s[86:87]
	s_mov_b32 m0, s11
	s_addc_u32 s25, s87, 0
	global_load_lds_dwordx4 v132, s[86:87]
	s_mov_b32 m0, s12
	s_nop 0
	global_load_lds_dwordx4 v130, s[24:25]
	s_mov_b32 m0, s13
	s_nop 0
	global_load_lds_dwordx4 v132, s[24:25]
	s_mov_b32 m0, s9
	s_nop 0
	global_load_lds_dwordx4 v130, s[90:91]
	s_mov_b32 m0, s14
	s_nop 0
	global_load_lds_dwordx4 v132, s[90:91]
	s_waitcnt vmcnt(8)
	s_waitcnt lgkmcnt(0)
	s_barrier
	s_setprio 1
	s_waitcnt lgkmcnt(0)
	v_mfma_f32_16x16x32_bf16 v[62:65], v[138:141], v[204:207], v[62:65]
	v_mfma_f32_16x16x32_bf16 v[58:61], v[154:157], v[204:207], v[58:61]
	v_mfma_f32_16x16x32_bf16 v[54:57], v[138:141], v[212:215], v[54:57]
	v_mfma_f32_16x16x32_bf16 v[50:53], v[154:157], v[212:215], v[50:53]
	v_mfma_f32_16x16x32_bf16 v[46:49], v[138:141], v[220:223], v[46:49]
	v_mfma_f32_16x16x32_bf16 v[42:45], v[154:157], v[220:223], v[42:45]
	v_mfma_f32_16x16x32_bf16 v[38:41], v[138:141], v[228:231], v[38:41]
	v_mfma_f32_16x16x32_bf16 v[34:37], v[154:157], v[228:231], v[34:37]
	v_mfma_f32_16x16x32_bf16 v[62:65], v[142:145], v[208:211], v[62:65]
	v_mfma_f32_16x16x32_bf16 v[58:61], v[158:161], v[208:211], v[58:61]
	v_mfma_f32_16x16x32_bf16 v[54:57], v[142:145], v[216:219], v[54:57]
	v_mfma_f32_16x16x32_bf16 v[50:53], v[158:161], v[216:219], v[50:53]
	v_mfma_f32_16x16x32_bf16 v[46:49], v[142:145], v[224:227], v[46:49]
	v_mfma_f32_16x16x32_bf16 v[42:45], v[158:161], v[224:227], v[42:45]
	v_mfma_f32_16x16x32_bf16 v[38:41], v[142:145], v[232:235], v[38:41]
	v_mfma_f32_16x16x32_bf16 v[34:37], v[158:161], v[232:235], v[34:37]
	s_setprio 0
	s_setprio 1
	v_mfma_f32_16x16x32_bf16 v[30:33], v[168:171], v[204:207], v[30:33]
	v_mfma_f32_16x16x32_bf16 v[26:29], v[196:199], v[204:207], v[26:29]
	v_mfma_f32_16x16x32_bf16 v[22:25], v[168:171], v[212:215], v[22:25]
	v_mfma_f32_16x16x32_bf16 v[18:21], v[196:199], v[212:215], v[18:21]
	v_mfma_f32_16x16x32_bf16 v[14:17], v[168:171], v[220:223], v[14:17]
	v_mfma_f32_16x16x32_bf16 v[10:13], v[196:199], v[220:223], v[10:13]
	v_mfma_f32_16x16x32_bf16 v[6:9], v[168:171], v[228:231], v[6:9]
	v_mfma_f32_16x16x32_bf16 v[2:5], v[196:199], v[228:231], v[2:5]
	v_mfma_f32_16x16x32_bf16 v[30:33], v[192:195], v[208:211], v[30:33]
	v_mfma_f32_16x16x32_bf16 v[26:29], v[200:203], v[208:211], v[26:29]
	v_mfma_f32_16x16x32_bf16 v[22:25], v[192:195], v[216:219], v[22:25]
	v_mfma_f32_16x16x32_bf16 v[18:21], v[200:203], v[216:219], v[18:21]
	v_mfma_f32_16x16x32_bf16 v[14:17], v[192:195], v[224:227], v[14:17]
	v_mfma_f32_16x16x32_bf16 v[10:13], v[200:203], v[224:227], v[10:13]
	v_mfma_f32_16x16x32_bf16 v[6:9], v[192:195], v[232:235], v[6:9]
	v_mfma_f32_16x16x32_bf16 v[2:5], v[200:203], v[232:235], v[2:5]
	s_setprio 0
	s_barrier
; #define PG8_STAGE(bufoff, gbase) do { _Pragma("unroll") for (int _i = 0; _i < 2; ++_i) \
;     __builtin_amdgcn_global_load_lds((const unsigned*)((const char*)(gbase) + voff[_i]), (LAS unsigned*)(lds + (bufoff) + ldsw + _i * 8192), 16, 0, 0); } while (0)
; #define PG8_LDA(dst, b, h) do { _Pragma("unroll") for (int m = 0; m < 4; ++m) _Pragma("unroll") for (int k = 0; k < 2; ++k) dst[m][k] = *(const LAS bf16x8*)(lds + PG8_SA(b, h) + aoff + m * 2048 + k * 1024); } while (0)
; #define PG8_LDB(dst, b, h) do { _Pragma("unroll") for (int n = 0; n < 2; ++n) _Pragma("unroll") for (int k = 0; k < 2; ++k) dst[n][k] = *(const LAS bf16x8*)(lds + PG8_SB(b, h) + boff + n * 2048 + k * 1024); } while (0)
; #define PG8_WAIT_V(n) asm volatile("s_waitcnt vmcnt(" #n ")" ::: "memory")
; #define PG8_WAIT_L(n) asm volatile("s_waitcnt lgkmcnt(" #n ")" ::: "memory")
; #define PG8_BAR __builtin_amdgcn_s_barrier()
; #define PG8_SCHED __builtin_amdgcn_sched_barrier(0)
; template <int EPI, bool ALIGN_EPI = true, bool SP2 = true>
; DI void gemm8_phase(const GemmArgs& g, char* lds_) {
;     ...
;         PG8_LDB(B0, 1, 0); PG8_LDB(B1, 1, 1); PG8_SCHED; PG8_LDA(At, 1, 0); PG8_STAGE(PG8_SA(0, 1), a2 + hstep);
;         PG8_WAIT_V(8); PG8_WAIT_L(0); PG8_BAR; PG8_MMA(0, 0, At, B0); PG8_MMA(0, 1, At, B1); PG8_BAR; PG8_SCHED;
;         PG8_LDA(At, 1, 1); PG8_STAGE(PG8_SB(1, 0), b3); PG8_STAGE(PG8_SB(1, 1), b3 + hstep); PG8_STAGE(PG8_SA(1, 0), a3);
;         PG8_WAIT_V(8); PG8_WAIT_L(0); PG8_BAR; PG8_MMA(1, 0, At, B0); PG8_MMA(1, 1, At, B1); PG8_BAR; PG8_SCHED;
	v_or_b32_e32 v0, 0x18000, v149
	v_add_u32_e32 v142, 0x18400, v149
	ds_read_b128 v[138:141], v0
	ds_read_b128 v[142:145], v142
	v_add_u32_e32 v0, 0x18800, v149
	v_add_u32_e32 v153, 0x18c00, v149
	ds_read_b128 v[154:157], v0
	ds_read_b128 v[158:161], v153
	v_or_b32_e32 v0, 0x1c000, v149
	v_add_u32_e32 v153, 0x1c400, v149
	ds_read_b128 v[168:171], v0
	ds_read_b128 v[192:195], v153
	v_add_u32_e32 v0, 0x1c800, v149
	v_add_u32_e32 v153, 0x1cc00, v149
	ds_read_b128 v[196:199], v0
	ds_read_b128 v[200:203], v153
	s_add_u32 s24, s90, 0x40000
	s_addc_u32 s25, s91, 0
	s_mov_b32 m0, s15
	ds_read_b128 v[204:207], v150 offset:32768
	ds_read_b128 v[208:211], v150 offset:33792
	ds_read_b128 v[212:215], v150 offset:34816
	ds_read_b128 v[216:219], v150 offset:35840
	ds_read_b128 v[220:223], v150 offset:36864
	ds_read_b128 v[224:227], v150 offset:37888
	ds_read_b128 v[228:231], v150 offset:38912
	ds_read_b128 v[232:235], v150 offset:39936
	global_load_lds_dwordx4 v130, s[24:25]
	s_mov_b32 m0, s16
	s_nop 0
	global_load_lds_dwordx4 v132, s[24:25]
	s_waitcnt vmcnt(8)
	s_waitcnt lgkmcnt(0)
	s_barrier
	s_setprio 1
	s_waitcnt lgkmcnt(0)
	v_mfma_f32_16x16x32_bf16 v[126:129], v[138:141], v[204:207], v[126:129]
	v_mfma_f32_16x16x32_bf16 v[122:125], v[154:157], v[204:207], v[122:125]
	v_mfma_f32_16x16x32_bf16 v[118:121], v[138:141], v[212:215], v[118:121]
	v_mfma_f32_16x16x32_bf16 v[114:117], v[154:157], v[212:215], v[114:117]
	v_mfma_f32_16x16x32_bf16 v[110:113], v[138:141], v[220:223], v[110:113]
	v_mfma_f32_16x16x32_bf16 v[106:109], v[154:157], v[220:223], v[106:109]
	v_mfma_f32_16x16x32_bf16 v[102:105], v[138:141], v[228:231], v[102:105]
	v_mfma_f32_16x16x32_bf16 v[98:101], v[154:157], v[228:231], v[98:101]
	v_mfma_f32_16x16x32_bf16 v[126:129], v[142:145], v[208:211], v[126:129]
	v_mfma_f32_16x16x32_bf16 v[122:125], v[158:161], v[208:211], v[122:125]
	v_mfma_f32_16x16x32_bf16 v[118:121], v[142:145], v[216:219], v[118:121]
	v_mfma_f32_16x16x32_bf16 v[114:117], v[158:161], v[216:219], v[114:117]
	v_mfma_f32_16x16x32_bf16 v[110:113], v[142:145], v[224:227], v[110:113]
	v_mfma_f32_16x16x32_bf16 v[106:109], v[158:161], v[224:227], v[106:109]
	v_mfma_f32_16x16x32_bf16 v[102:105], v[142:145], v[232:235], v[102:105]
	v_mfma_f32_16x16x32_bf16 v[98:101], v[158:161], v[232:235], v[98:101]
	s_setprio 0
	s_setprio 1
	v_mfma_f32_16x16x32_bf16 v[94:97], v[168:171], v[204:207], v[94:97]
	v_mfma_f32_16x16x32_bf16 v[90:93], v[196:199], v[204:207], v[90:93]
	v_mfma_f32_16x16x32_bf16 v[86:89], v[168:171], v[212:215], v[86:89]
	v_mfma_f32_16x16x32_bf16 v[82:85], v[196:199], v[212:215], v[82:85]
	v_mfma_f32_16x16x32_bf16 v[78:81], v[168:171], v[220:223], v[78:81]
	v_mfma_f32_16x16x32_bf16 v[74:77], v[196:199], v[220:223], v[74:77]
	v_mfma_f32_16x16x32_bf16 v[70:73], v[168:171], v[228:231], v[70:73]
	v_mfma_f32_16x16x32_bf16 v[66:69], v[196:199], v[228:231], v[66:69]
	v_mfma_f32_16x16x32_bf16 v[94:97], v[192:195], v[208:211], v[94:97]
	v_mfma_f32_16x16x32_bf16 v[90:93], v[200:203], v[208:211], v[90:93]
	v_mfma_f32_16x16x32_bf16 v[86:89], v[192:195], v[216:219], v[86:89]
	v_mfma_f32_16x16x32_bf16 v[82:85], v[200:203], v[216:219], v[82:85]
	v_mfma_f32_16x16x32_bf16 v[78:81], v[192:195], v[224:227], v[78:81]
	v_mfma_f32_16x16x32_bf16 v[74:77], v[200:203], v[224:227], v[74:77]
	v_mfma_f32_16x16x32_bf16 v[70:73], v[192:195], v[232:235], v[70:73]
	v_mfma_f32_16x16x32_bf16 v[66:69], v[200:203], v[232:235], v[66:69]
	s_setprio 0
	s_barrier
	s_mov_b32 m0, s19
	s_add_u32 s24, s86, 0x40080
	ds_read_b128 v[204:207], v150 offset:49152
	ds_read_b128 v[208:211], v150 offset:50176
	ds_read_b128 v[212:215], v150 offset:51200
	ds_read_b128 v[216:219], v150 offset:52224
	ds_read_b128 v[220:223], v150 offset:53248
	ds_read_b128 v[224:227], v150 offset:54272
	ds_read_b128 v[228:231], v150 offset:55296
	ds_read_b128 v[232:235], v150 offset:56320
	global_load_lds_dwordx4 v164, s[86:87]
	s_mov_b32 m0, s28
	s_addc_u32 s25, s87, 0
	global_load_lds_dwordx4 v165, s[86:87]
	s_mov_b32 m0, s69
	s_nop 0
	global_load_lds_dwordx4 v130, s[24:25]
	s_mov_b32 m0, s20
	s_nop 0
	global_load_lds_dwordx4 v132, s[24:25]
	s_mov_b32 m0, s57
	s_nop 0
	global_load_lds_dwordx4 v164, s[90:91]
	s_mov_b32 m0, s68
	s_nop 0
	global_load_lds_dwordx4 v165, s[90:91]
	s_waitcnt vmcnt(8)
	s_waitcnt lgkmcnt(0)
	s_barrier
	s_setprio 1
	s_waitcnt lgkmcnt(0)
	v_mfma_f32_16x16x32_bf16 v[62:65], v[138:141], v[204:207], v[62:65]
	v_mfma_f32_16x16x32_bf16 v[58:61], v[154:157], v[204:207], v[58:61]
	v_mfma_f32_16x16x32_bf16 v[54:57], v[138:141], v[212:215], v[54:57]
	v_mfma_f32_16x16x32_bf16 v[50:53], v[154:157], v[212:215], v[50:53]
	v_mfma_f32_16x16x32_bf16 v[46:49], v[138:141], v[220:223], v[46:49]
	v_mfma_f32_16x16x32_bf16 v[42:45], v[154:157], v[220:223], v[42:45]
	v_mfma_f32_16x16x32_bf16 v[38:41], v[138:141], v[228:231], v[38:41]
	v_mfma_f32_16x16x32_bf16 v[34:37], v[154:157], v[228:231], v[34:37]
	v_mfma_f32_16x16x32_bf16 v[62:65], v[142:145], v[208:211], v[62:65]
	v_mfma_f32_16x16x32_bf16 v[58:61], v[158:161], v[208:211], v[58:61]
	v_mfma_f32_16x16x32_bf16 v[54:57], v[142:145], v[216:219], v[54:57]
	v_mfma_f32_16x16x32_bf16 v[50:53], v[158:161], v[216:219], v[50:53]
	v_mfma_f32_16x16x32_bf16 v[46:49], v[142:145], v[224:227], v[46:49]
	v_mfma_f32_16x16x32_bf16 v[42:45], v[158:161], v[224:227], v[42:45]
	v_mfma_f32_16x16x32_bf16 v[38:41], v[142:145], v[232:235], v[38:41]
	v_mfma_f32_16x16x32_bf16 v[34:37], v[158:161], v[232:235], v[34:37]
	s_setprio 0
	s_setprio 1
	v_mfma_f32_16x16x32_bf16 v[30:33], v[168:171], v[204:207], v[30:33]
	v_mfma_f32_16x16x32_bf16 v[26:29], v[196:199], v[204:207], v[26:29]
	v_mfma_f32_16x16x32_bf16 v[22:25], v[168:171], v[212:215], v[22:25]
	v_mfma_f32_16x16x32_bf16 v[18:21], v[196:199], v[212:215], v[18:21]
	v_mfma_f32_16x16x32_bf16 v[14:17], v[168:171], v[220:223], v[14:17]
	v_mfma_f32_16x16x32_bf16 v[10:13], v[196:199], v[220:223], v[10:13]
	v_mfma_f32_16x16x32_bf16 v[6:9], v[168:171], v[228:231], v[6:9]
	v_mfma_f32_16x16x32_bf16 v[2:5], v[196:199], v[228:231], v[2:5]
	v_mfma_f32_16x16x32_bf16 v[30:33], v[192:195], v[208:211], v[30:33]
	v_mfma_f32_16x16x32_bf16 v[26:29], v[200:203], v[208:211], v[26:29]
	v_mfma_f32_16x16x32_bf16 v[22:25], v[192:195], v[216:219], v[22:25]
	v_mfma_f32_16x16x32_bf16 v[18:21], v[200:203], v[216:219], v[18:21]
	v_mfma_f32_16x16x32_bf16 v[14:17], v[192:195], v[224:227], v[14:17]
	v_mfma_f32_16x16x32_bf16 v[10:13], v[200:203], v[224:227], v[10:13]
	v_mfma_f32_16x16x32_bf16 v[6:9], v[192:195], v[232:235], v[6:9]
	v_mfma_f32_16x16x32_bf16 v[2:5], v[200:203], v[232:235], v[2:5]
	s_setprio 0
	s_barrier
	s_add_i32 vcc_lo, vcc_lo, 2
	s_add_u32 s50, s50, 0x100
	s_addc_u32 s51, s51, 0
	s_cmp_gt_u32 vcc_lo, 13
	s_mov_b64 s[34:35], s[40:41]
	s_cbranch_scc0 .LBB0_381
	s_and_b64 vcc, exec, s[42:43]
	s_cbranch_vccz .LBB0_384
	s_barrier

; #define PG8_WAIT_V(n) asm volatile("s_waitcnt vmcnt(" #n ")" ::: "memory")
; #define PG8_BAR __builtin_amdgcn_s_barrier()
; template <int EPI, bool ALIGN_EPI = true, bool SP2 = true>
; DI void gemm8_phase(const GemmArgs& g, char* lds_) {
;     ...
;   f32x4 acc[2][2][4][2];
; #pragma unroll
;   for (int a = 0; a < 2; ++a)
; #pragma unroll
;     for (int b = 0; b < 2; ++b)
; #pragma unroll
;       for (int m = 0; m < 4; ++m)
; #pragma unroll
;         for (int n = 0; n < 2; ++n) acc[a][b][m][n] = f32x4{0.f, 0.f, 0.f, 0.f};
;   bf16x8 At[4][2], B0[2][2], B1[2][2];
;   const char* cA = (const char*)g.A0 + (size_t)cpm * tstep;
;   const char* cB = (const char*)g.Bt0 + (size_t)cpn * tstep;
;   PG8_WAIT_V(0);
;   __syncthreads();
;   if constexpr (SP2) {
;     PG8_STAGE(PG8_SB(0, 0), cB); PG8_STAGE(PG8_SB(0, 1), cB + hstep); PG8_STAGE(PG8_SA(0, 0), cA); PG8_STAGE(PG8_SA(0, 1), cA + hstep);
;     if (wr == 1) PG8_BAR;
;     PG8_WAIT_V(2); PG8_BAR;
;     PG8_STAGE(PG8_SB(1, 0), cB + kstep); PG8_STAGE(PG8_SA(1, 0), cA + kstep); PG8_STAGE(PG8_SB(1, 1), cB + hstep + kstep);
;     PG8_WAIT_V(6); PG8_BAR;
;   } else {
;     PG8_STAGE(PG8_SB(0, 0), cB); PG8_STAGE(PG8_SA(0, 0), cA); PG8_STAGE(PG8_SB(0, 1), cB + hstep); PG8_STAGE(PG8_SA(0, 1), cA + hstep);
;     if (wr == 1) PG8_BAR;
;     PG8_WAIT_V(4); PG8_BAR;
;     PG8_STAGE(PG8_SB(1, 0), cB + kstep); PG8_STAGE(PG8_SA(1, 0), cA + kstep); PG8_STAGE(PG8_SB(1, 1), cB + hstep + kstep);
;     PG8_WAIT_V(6); PG8_BAR;
;   }
;   for (;;) {
;     const int nid = (int)blockIdx.x + (ui + 1) * G;
;     const bool has_next = nid < total;
;     if (has_next) tile_map(nid, g.NTm, g.NTn, npm, npn, g.gm);
;     const char* nA = has_next ? (const char*)g.A0 + (size_t)npm * tstep : cA;
;     const char* nB = has_next ? (const char*)g.Bt0 + (size_t)npn * tstep : cB;
; #pragma unroll 1
;     for (int t = 0; t < nt; t += 2) {
;       const bool last = (t == nt - 2);
;       const char* a1 = cA + (size_t)(t + 1) * kstep;
;       const char* a2 = last ? nA : cA + (size_t)(t + 2) * kstep;
;       const char* b2 = last ? nB : cB + (size_t)(t + 2) * kstep;
;       const char* a3 = a2 + kstep; const char* b3 = b2 + kstep;
;       if constexpr (SP2) {
;         const bool relax = EPI_VM > 0 && t == 0 && ui > 0;
;         PG8_LDB(B0, 0, 0); PG8_LDB(B1, 0, 1); PG8_SCHED; PG8_LDA(At, 0, 0); PG8_STAGE(PG8_SA(1, 1), a1 + hstep);
.LBB0_572:
	s_ashr_i32 s45, s44, 31
	s_lshl_b64 s[24:25], s[44:45], 19
	s_add_u32 s34, s7, s24
	s_addc_u32 s35, s8, s25
	s_and_b64 s[24:25], s[84:85], exec
	s_cselect_b32 s45, s35, s41
	s_cselect_b32 s47, s34, s40
	s_add_u32 s50, s40, 0x100
	v_mov_b32_e32 v2, 0
	s_addc_u32 s51, s41, 0
	s_mov_b32 s69, -2
	v_mov_b32_e32 v3, v2
	v_mov_b32_e32 v4, v2
	v_mov_b32_e32 v5, v2
	v_mov_b32_e32 v6, v2
	v_mov_b32_e32 v7, v2
	v_mov_b32_e32 v8, v2
	v_mov_b32_e32 v9, v2
	v_mov_b32_e32 v10, v2
	v_mov_b32_e32 v11, v2
	v_mov_b32_e32 v12, v2
	v_mov_b32_e32 v13, v2
	v_mov_b32_e32 v14, v2
	v_mov_b32_e32 v15, v2
	v_mov_b32_e32 v16, v2
	v_mov_b32_e32 v17, v2
	v_mov_b32_e32 v18, v2
	v_mov_b32_e32 v19, v2
	v_mov_b32_e32 v20, v2
	v_mov_b32_e32 v21, v2
	v_mov_b32_e32 v22, v2
	v_mov_b32_e32 v23, v2
	v_mov_b32_e32 v24, v2
	v_mov_b32_e32 v25, v2
	v_mov_b32_e32 v26, v2
	v_mov_b32_e32 v27, v2
	v_mov_b32_e32 v28, v2
	v_mov_b32_e32 v29, v2
	v_mov_b32_e32 v30, v2
	v_mov_b32_e32 v31, v2
	v_mov_b32_e32 v32, v2
	v_mov_b32_e32 v33, v2
	v_mov_b32_e32 v34, v2
	v_mov_b32_e32 v35, v2
	v_mov_b32_e32 v36, v2
	v_mov_b32_e32 v37, v2
	v_mov_b32_e32 v46, v2
	v_mov_b32_e32 v47, v2
	v_mov_b32_e32 v48, v2
	v_mov_b32_e32 v49, v2
	v_mov_b32_e32 v38, v2
	v_mov_b32_e32 v39, v2
	v_mov_b32_e32 v40, v2
	v_mov_b32_e32 v41, v2
	v_mov_b32_e32 v54, v2
	v_mov_b32_e32 v55, v2
	v_mov_b32_e32 v56, v2
	v_mov_b32_e32 v57, v2
	v_mov_b32_e32 v42, v2
	v_mov_b32_e32 v43, v2
	v_mov_b32_e32 v44, v2
	v_mov_b32_e32 v45, v2
	v_mov_b32_e32 v58, v2
	v_mov_b32_e32 v59, v2
	v_mov_b32_e32 v60, v2
	v_mov_b32_e32 v61, v2
	v_mov_b32_e32 v50, v2
	v_mov_b32_e32 v51, v2
	v_mov_b32_e32 v52, v2
	v_mov_b32_e32 v53, v2
	v_mov_b32_e32 v62, v2
	v_mov_b32_e32 v63, v2
	v_mov_b32_e32 v64, v2
	v_mov_b32_e32 v65, v2
	v_mov_b32_e32 v66, v2
	v_mov_b32_e32 v67, v2
	v_mov_b32_e32 v68, v2
	v_mov_b32_e32 v69, v2
	v_mov_b32_e32 v70, v2
	v_mov_b32_e32 v71, v2
	v_mov_b32_e32 v72, v2
	v_mov_b32_e32 v73, v2
	v_mov_b32_e32 v74, v2
	v_mov_b32_e32 v75, v2
	v_mov_b32_e32 v76, v2
	v_mov_b32_e32 v77, v2
	v_mov_b32_e32 v78, v2
	v_mov_b32_e32 v79, v2
	v_mov_b32_e32 v80, v2
	v_mov_b32_e32 v81, v2
	v_mov_b32_e32 v82, v2
	v_mov_b32_e32 v83, v2
	v_mov_b32_e32 v84, v2
	v_mov_b32_e32 v85, v2
	v_mov_b32_e32 v86, v2
	v_mov_b32_e32 v87, v2
	v_mov_b32_e32 v88, v2
	v_mov_b32_e32 v89, v2
	v_mov_b32_e32 v90, v2
	v_mov_b32_e32 v91, v2
	v_mov_b32_e32 v92, v2
	v_mov_b32_e32 v93, v2
	v_mov_b32_e32 v94, v2
	v_mov_b32_e32 v95, v2
	v_mov_b32_e32 v96, v2
	v_mov_b32_e32 v97, v2
	v_mov_b32_e32 v98, v2
	v_mov_b32_e32 v99, v2
	v_mov_b32_e32 v100, v2
	v_mov_b32_e32 v101, v2
	v_mov_b32_e32 v110, v2
	v_mov_b32_e32 v111, v2
	v_mov_b32_e32 v112, v2
	v_mov_b32_e32 v113, v2
	v_mov_b32_e32 v102, v2
	v_mov_b32_e32 v103, v2
	v_mov_b32_e32 v104, v2
	v_mov_b32_e32 v105, v2
	v_mov_b32_e32 v118, v2
	v_mov_b32_e32 v119, v2
	v_mov_b32_e32 v120, v2
	v_mov_b32_e32 v121, v2
	v_mov_b32_e32 v106, v2
	v_mov_b32_e32 v107, v2
	v_mov_b32_e32 v108, v2
	v_mov_b32_e32 v109, v2
	v_mov_b32_e32 v122, v2
	v_mov_b32_e32 v123, v2
	v_mov_b32_e32 v124, v2
	v_mov_b32_e32 v125, v2
	v_mov_b32_e32 v114, v2
	v_mov_b32_e32 v115, v2
	v_mov_b32_e32 v116, v2
	v_mov_b32_e32 v117, v2
	v_mov_b32_e32 v126, v2
	v_mov_b32_e32 v127, v2
	v_mov_b32_e32 v128, v2
	v_mov_b32_e32 v129, v2
	v_add_u32_e32 v164, 0x80, v130
	v_add_u32_e32 v165, 0x80, v132
.LBB0_573:
	v_or_b32_e32 v0, 0x10000, v142
	v_add_u32_e32 v138, 0x10400, v142
	ds_read_b128 v[146:149], v0
	ds_read_b128 v[150:153], v138
	v_add_u32_e32 v0, 0x10800, v142
	v_add_u32_e32 v138, 0x10c00, v142
	ds_read_b128 v[154:157], v0
	ds_read_b128 v[158:161], v138
	v_or_b32_e32 v0, 0x14000, v142
	v_add_u32_e32 v138, 0x14400, v142
	ds_read_b128 v[168:171], v0
	ds_read_b128 v[192:195], v138
	v_add_u32_e32 v0, 0x14800, v142
	v_add_u32_e32 v138, 0x14c00, v142
	ds_read_b128 v[196:199], v0
	ds_read_b128 v[200:203], v138
	s_add_u32 s40, s38, 0x100
	s_addc_u32 s41, s39, 0
	s_cmp_eq_u32 s69, 12
	s_cselect_b32 s91, s49, s41
	s_cselect_b32 s90, s48, s40
	s_cselect_b32 s87, s45, s51
	s_cselect_b32 s86, s47, s50
	s_add_i32 m0, s9, 0xc000
	ds_read_b128 v[204:207], v141
	ds_read_b128 v[208:211], v141 offset:1024
	ds_read_b128 v[212:215], v141 offset:2048
	ds_read_b128 v[216:219], v141 offset:3072
	ds_read_b128 v[220:223], v141 offset:4096
	ds_read_b128 v[224:227], v141 offset:5120
	ds_read_b128 v[228:231], v141 offset:6144
	ds_read_b128 v[232:235], v141 offset:7168
	global_load_lds_dwordx4 v134, s[38:39]
	s_add_i32 m0, s9, 0xe000
	s_nop 0
	global_load_lds_dwordx4 v136, s[38:39]
	s_waitcnt vmcnt(8)
	s_waitcnt lgkmcnt(0)
	s_barrier
; #define PG8_STAGE(bufoff, gbase) do { _Pragma("unroll") for (int _i = 0; _i < 2; ++_i) \
;     __builtin_amdgcn_global_load_lds((const unsigned*)((const char*)(gbase) + voff[_i]), (LAS unsigned*)(lds + (bufoff) + ldsw + _i * 8192), 16, 0, 0); } while (0)
; #define PG8_LDA(dst, b, h) do { _Pragma("unroll") for (int m = 0; m < 4; ++m) _Pragma("unroll") for (int k = 0; k < 2; ++k) dst[m][k] = *(const LAS bf16x8*)(lds + PG8_SA(b, h) + aoff + m * 2048 + k * 1024); } while (0)
; #define PG8_WAIT_V(n) asm volatile("s_waitcnt vmcnt(" #n ")" ::: "memory")
; #define PG8_WAIT_L(n) asm volatile("s_waitcnt lgkmcnt(" #n ")" ::: "memory")
; #define PG8_BAR __builtin_amdgcn_s_barrier()
; #define PG8_SCHED __builtin_amdgcn_sched_barrier(0)
; template <int EPI, bool ALIGN_EPI = true, bool SP2 = true>
; DI void gemm8_phase(const GemmArgs& g, char* lds_) {
;     ...
;         PG8_WAIT_L(0); PG8_BAR; PG8_MMA(0, 0, At, B0); PG8_MMA(0, 1, At, B1); PG8_BAR; PG8_SCHED;
;         PG8_LDA(At, 0, 1); PG8_STAGE(PG8_SB(0, 0), b2); PG8_STAGE(PG8_SB(0, 1), b2 + hstep); PG8_STAGE(PG8_SA(0, 0), a2);
;         if (relax) PG8_WAIT_V(24); else PG8_WAIT_V(8);
;         PG8_WAIT_L(0); PG8_BAR; PG8_MMA(1, 0, At, B0); PG8_MMA(1, 1, At, B1); PG8_BAR; PG8_SCHED;
	s_setprio 1
	s_waitcnt lgkmcnt(0)
	v_mfma_f32_16x16x32_bf16 v[126:129], v[146:149], v[204:207], v[126:129]
	v_mfma_f32_16x16x32_bf16 v[114:117], v[154:157], v[204:207], v[114:117]
	v_mfma_f32_16x16x32_bf16 v[122:125], v[146:149], v[212:215], v[122:125]
	v_mfma_f32_16x16x32_bf16 v[106:109], v[154:157], v[212:215], v[106:109]
	v_mfma_f32_16x16x32_bf16 v[118:121], v[146:149], v[220:223], v[118:121]
	v_mfma_f32_16x16x32_bf16 v[102:105], v[154:157], v[220:223], v[102:105]
	v_mfma_f32_16x16x32_bf16 v[110:113], v[146:149], v[228:231], v[110:113]
	v_mfma_f32_16x16x32_bf16 v[98:101], v[154:157], v[228:231], v[98:101]
	v_mfma_f32_16x16x32_bf16 v[126:129], v[150:153], v[208:211], v[126:129]
	v_mfma_f32_16x16x32_bf16 v[114:117], v[158:161], v[208:211], v[114:117]
	v_mfma_f32_16x16x32_bf16 v[122:125], v[150:153], v[216:219], v[122:125]
	v_mfma_f32_16x16x32_bf16 v[106:109], v[158:161], v[216:219], v[106:109]
	v_mfma_f32_16x16x32_bf16 v[118:121], v[150:153], v[224:227], v[118:121]
	v_mfma_f32_16x16x32_bf16 v[102:105], v[158:161], v[224:227], v[102:105]
	v_mfma_f32_16x16x32_bf16 v[110:113], v[150:153], v[232:235], v[110:113]
	v_mfma_f32_16x16x32_bf16 v[98:101], v[158:161], v[232:235], v[98:101]
	s_setprio 0
	s_setprio 1
	v_mfma_f32_16x16x32_bf16 v[94:97], v[168:171], v[204:207], v[94:97]
	v_mfma_f32_16x16x32_bf16 v[90:93], v[196:199], v[204:207], v[90:93]
	v_mfma_f32_16x16x32_bf16 v[86:89], v[168:171], v[212:215], v[86:89]
	v_mfma_f32_16x16x32_bf16 v[82:85], v[196:199], v[212:215], v[82:85]
	v_mfma_f32_16x16x32_bf16 v[78:81], v[168:171], v[220:223], v[78:81]
	v_mfma_f32_16x16x32_bf16 v[74:77], v[196:199], v[220:223], v[74:77]
	v_mfma_f32_16x16x32_bf16 v[70:73], v[168:171], v[228:231], v[70:73]
	v_mfma_f32_16x16x32_bf16 v[66:69], v[196:199], v[228:231], v[66:69]
	v_mfma_f32_16x16x32_bf16 v[94:97], v[192:195], v[208:211], v[94:97]
	v_mfma_f32_16x16x32_bf16 v[90:93], v[200:203], v[208:211], v[90:93]
	v_mfma_f32_16x16x32_bf16 v[86:89], v[192:195], v[216:219], v[86:89]
	v_mfma_f32_16x16x32_bf16 v[82:85], v[200:203], v[216:219], v[82:85]
	v_mfma_f32_16x16x32_bf16 v[78:81], v[192:195], v[224:227], v[78:81]
	v_mfma_f32_16x16x32_bf16 v[74:77], v[200:203], v[224:227], v[74:77]
	v_mfma_f32_16x16x32_bf16 v[70:73], v[192:195], v[232:235], v[70:73]
	v_mfma_f32_16x16x32_bf16 v[66:69], v[200:203], v[232:235], v[66:69]
	s_setprio 0
	s_barrier
	s_mov_b32 m0, s10
	s_add_u32 s24, s86, 0x40000
	ds_read_b128 v[204:207], v141 offset:16384
	ds_read_b128 v[208:211], v141 offset:17408
	ds_read_b128 v[212:215], v141 offset:18432
	ds_read_b128 v[216:219], v141 offset:19456
	ds_read_b128 v[220:223], v141 offset:20480
	ds_read_b128 v[224:227], v141 offset:21504
	ds_read_b128 v[228:231], v141 offset:22528
	ds_read_b128 v[232:235], v141 offset:23552
	global_load_lds_dwordx4 v130, s[86:87]
	s_mov_b32 m0, s11
	s_addc_u32 s25, s87, 0
	global_load_lds_dwordx4 v132, s[86:87]
	s_mov_b32 m0, s12
	s_nop 0
	global_load_lds_dwordx4 v130, s[24:25]
	s_mov_b32 m0, s13
	s_nop 0
	global_load_lds_dwordx4 v132, s[24:25]
	s_mov_b32 m0, s9
	s_nop 0
	global_load_lds_dwordx4 v130, s[90:91]
	s_mov_b32 m0, s14
	s_nop 0
	global_load_lds_dwordx4 v132, s[90:91]
	s_waitcnt vmcnt(8)
	s_waitcnt lgkmcnt(0)
	s_barrier
	s_setprio 1
	s_waitcnt lgkmcnt(0)
	v_mfma_f32_16x16x32_bf16 v[62:65], v[146:149], v[204:207], v[62:65]
	v_mfma_f32_16x16x32_bf16 v[50:53], v[154:157], v[204:207], v[50:53]
	v_mfma_f32_16x16x32_bf16 v[58:61], v[146:149], v[212:215], v[58:61]
	v_mfma_f32_16x16x32_bf16 v[42:45], v[154:157], v[212:215], v[42:45]
	v_mfma_f32_16x16x32_bf16 v[54:57], v[146:149], v[220:223], v[54:57]
	v_mfma_f32_16x16x32_bf16 v[38:41], v[154:157], v[220:223], v[38:41]
	v_mfma_f32_16x16x32_bf16 v[46:49], v[146:149], v[228:231], v[46:49]
	v_mfma_f32_16x16x32_bf16 v[34:37], v[154:157], v[228:231], v[34:37]
	v_mfma_f32_16x16x32_bf16 v[62:65], v[150:153], v[208:211], v[62:65]
	v_mfma_f32_16x16x32_bf16 v[50:53], v[158:161], v[208:211], v[50:53]
	v_mfma_f32_16x16x32_bf16 v[58:61], v[150:153], v[216:219], v[58:61]
	v_mfma_f32_16x16x32_bf16 v[42:45], v[158:161], v[216:219], v[42:45]
	v_mfma_f32_16x16x32_bf16 v[54:57], v[150:153], v[224:227], v[54:57]
	v_mfma_f32_16x16x32_bf16 v[38:41], v[158:161], v[224:227], v[38:41]
	v_mfma_f32_16x16x32_bf16 v[46:49], v[150:153], v[232:235], v[46:49]
	v_mfma_f32_16x16x32_bf16 v[34:37], v[158:161], v[232:235], v[34:37]
	s_setprio 0
	s_setprio 1
	v_mfma_f32_16x16x32_bf16 v[30:33], v[168:171], v[204:207], v[30:33]
	v_mfma_f32_16x16x32_bf16 v[26:29], v[196:199], v[204:207], v[26:29]
	v_mfma_f32_16x16x32_bf16 v[22:25], v[168:171], v[212:215], v[22:25]
	v_mfma_f32_16x16x32_bf16 v[18:21], v[196:199], v[212:215], v[18:21]
	v_mfma_f32_16x16x32_bf16 v[14:17], v[168:171], v[220:223], v[14:17]
	v_mfma_f32_16x16x32_bf16 v[10:13], v[196:199], v[220:223], v[10:13]
	v_mfma_f32_16x16x32_bf16 v[6:9], v[168:171], v[228:231], v[6:9]
	v_mfma_f32_16x16x32_bf16 v[2:5], v[196:199], v[228:231], v[2:5]
	v_mfma_f32_16x16x32_bf16 v[30:33], v[192:195], v[208:211], v[30:33]
	v_mfma_f32_16x16x32_bf16 v[26:29], v[200:203], v[208:211], v[26:29]
	v_mfma_f32_16x16x32_bf16 v[22:25], v[192:195], v[216:219], v[22:25]
	v_mfma_f32_16x16x32_bf16 v[18:21], v[200:203], v[216:219], v[18:21]
	v_mfma_f32_16x16x32_bf16 v[14:17], v[192:195], v[224:227], v[14:17]
	v_mfma_f32_16x16x32_bf16 v[10:13], v[200:203], v[224:227], v[10:13]
	v_mfma_f32_16x16x32_bf16 v[6:9], v[192:195], v[232:235], v[6:9]
	v_mfma_f32_16x16x32_bf16 v[2:5], v[200:203], v[232:235], v[2:5]
	s_setprio 0
	s_barrier
; #define PG8_STAGE(bufoff, gbase) do { _Pragma("unroll") for (int _i = 0; _i < 2; ++_i) \
;     __builtin_amdgcn_global_load_lds((const unsigned*)((const char*)(gbase) + voff[_i]), (LAS unsigned*)(lds + (bufoff) + ldsw + _i * 8192), 16, 0, 0); } while (0)
; #define PG8_LDA(dst, b, h) do { _Pragma("unroll") for (int m = 0; m < 4; ++m) _Pragma("unroll") for (int k = 0; k < 2; ++k) dst[m][k] = *(const LAS bf16x8*)(lds + PG8_SA(b, h) + aoff + m * 2048 + k * 1024); } while (0)
; #define PG8_LDB(dst, b, h) do { _Pragma("unroll") for (int n = 0; n < 2; ++n) _Pragma("unroll") for (int k = 0; k < 2; ++k) dst[n][k] = *(const LAS bf16x8*)(lds + PG8_SB(b, h) + boff + n * 2048 + k * 1024); } while (0)
; #define PG8_WAIT_V(n) asm volatile("s_waitcnt vmcnt(" #n ")" ::: "memory")
; #define PG8_WAIT_L(n) asm volatile("s_waitcnt lgkmcnt(" #n ")" ::: "memory")
; #define PG8_BAR __builtin_amdgcn_s_barrier()
; #define PG8_SCHED __builtin_amdgcn_sched_barrier(0)
; template <int EPI, bool ALIGN_EPI = true, bool SP2 = true>
; DI void gemm8_phase(const GemmArgs& g, char* lds_) {
;     ...
;         PG8_LDB(B0, 1, 0); PG8_LDB(B1, 1, 1); PG8_SCHED; PG8_LDA(At, 1, 0); PG8_STAGE(PG8_SA(0, 1), a2 + hstep);
;         PG8_WAIT_V(8); PG8_WAIT_L(0); PG8_BAR; PG8_MMA(0, 0, At, B0); PG8_MMA(0, 1, At, B1); PG8_BAR; PG8_SCHED;
;         PG8_LDA(At, 1, 1); PG8_STAGE(PG8_SB(1, 0), b3); PG8_STAGE(PG8_SB(1, 1), b3 + hstep); PG8_STAGE(PG8_SA(1, 0), a3);
;         PG8_WAIT_V(8); PG8_WAIT_L(0); PG8_BAR; PG8_MMA(1, 0, At, B0); PG8_MMA(1, 1, At, B1); PG8_BAR; PG8_SCHED;
	v_or_b32_e32 v0, 0x18000, v142
	v_add_u32_e32 v145, 0x18400, v142
	ds_read_b128 v[146:149], v0
	ds_read_b128 v[150:153], v145
	v_add_u32_e32 v0, 0x18800, v142
	v_add_u32_e32 v145, 0x18c00, v142
	ds_read_b128 v[154:157], v0
	ds_read_b128 v[158:161], v145
	v_or_b32_e32 v0, 0x1c000, v142
	v_add_u32_e32 v145, 0x1c400, v142
	ds_read_b128 v[168:171], v0
	ds_read_b128 v[192:195], v145
	v_add_u32_e32 v0, 0x1c800, v142
	v_add_u32_e32 v145, 0x1cc00, v142
	ds_read_b128 v[196:199], v0
	ds_read_b128 v[200:203], v145
	s_add_u32 s24, s90, 0x40000
	s_addc_u32 s25, s91, 0
	s_mov_b32 m0, s15
	ds_read_b128 v[204:207], v141 offset:32768
	ds_read_b128 v[208:211], v141 offset:33792
	ds_read_b128 v[212:215], v141 offset:34816
	ds_read_b128 v[216:219], v141 offset:35840
	ds_read_b128 v[220:223], v141 offset:36864
	ds_read_b128 v[224:227], v141 offset:37888
	ds_read_b128 v[228:231], v141 offset:38912
	ds_read_b128 v[232:235], v141 offset:39936
	global_load_lds_dwordx4 v130, s[24:25]
	s_mov_b32 m0, s16
	s_nop 0
	global_load_lds_dwordx4 v132, s[24:25]
	s_waitcnt vmcnt(8)
	s_waitcnt lgkmcnt(0)
	s_barrier
	s_setprio 1
	s_waitcnt lgkmcnt(0)
	v_mfma_f32_16x16x32_bf16 v[126:129], v[146:149], v[204:207], v[126:129]
	v_mfma_f32_16x16x32_bf16 v[114:117], v[154:157], v[204:207], v[114:117]
	v_mfma_f32_16x16x32_bf16 v[122:125], v[146:149], v[212:215], v[122:125]
	v_mfma_f32_16x16x32_bf16 v[106:109], v[154:157], v[212:215], v[106:109]
	v_mfma_f32_16x16x32_bf16 v[118:121], v[146:149], v[220:223], v[118:121]
	v_mfma_f32_16x16x32_bf16 v[102:105], v[154:157], v[220:223], v[102:105]
	v_mfma_f32_16x16x32_bf16 v[110:113], v[146:149], v[228:231], v[110:113]
	v_mfma_f32_16x16x32_bf16 v[98:101], v[154:157], v[228:231], v[98:101]
	v_mfma_f32_16x16x32_bf16 v[126:129], v[150:153], v[208:211], v[126:129]
	v_mfma_f32_16x16x32_bf16 v[114:117], v[158:161], v[208:211], v[114:117]
	v_mfma_f32_16x16x32_bf16 v[122:125], v[150:153], v[216:219], v[122:125]
	v_mfma_f32_16x16x32_bf16 v[106:109], v[158:161], v[216:219], v[106:109]
	v_mfma_f32_16x16x32_bf16 v[118:121], v[150:153], v[224:227], v[118:121]
	v_mfma_f32_16x16x32_bf16 v[102:105], v[158:161], v[224:227], v[102:105]
	v_mfma_f32_16x16x32_bf16 v[110:113], v[150:153], v[232:235], v[110:113]
	v_mfma_f32_16x16x32_bf16 v[98:101], v[158:161], v[232:235], v[98:101]
	s_setprio 0
	s_setprio 1
	v_mfma_f32_16x16x32_bf16 v[94:97], v[168:171], v[204:207], v[94:97]
	v_mfma_f32_16x16x32_bf16 v[90:93], v[196:199], v[204:207], v[90:93]
	v_mfma_f32_16x16x32_bf16 v[86:89], v[168:171], v[212:215], v[86:89]
	v_mfma_f32_16x16x32_bf16 v[82:85], v[196:199], v[212:215], v[82:85]
	v_mfma_f32_16x16x32_bf16 v[78:81], v[168:171], v[220:223], v[78:81]
	v_mfma_f32_16x16x32_bf16 v[74:77], v[196:199], v[220:223], v[74:77]
	v_mfma_f32_16x16x32_bf16 v[70:73], v[168:171], v[228:231], v[70:73]
	v_mfma_f32_16x16x32_bf16 v[66:69], v[196:199], v[228:231], v[66:69]
	v_mfma_f32_16x16x32_bf16 v[94:97], v[192:195], v[208:211], v[94:97]
	v_mfma_f32_16x16x32_bf16 v[90:93], v[200:203], v[208:211], v[90:93]
	v_mfma_f32_16x16x32_bf16 v[86:89], v[192:195], v[216:219], v[86:89]
	v_mfma_f32_16x16x32_bf16 v[82:85], v[200:203], v[216:219], v[82:85]
	v_mfma_f32_16x16x32_bf16 v[78:81], v[192:195], v[224:227], v[78:81]
	v_mfma_f32_16x16x32_bf16 v[74:77], v[200:203], v[224:227], v[74:77]
	v_mfma_f32_16x16x32_bf16 v[70:73], v[192:195], v[232:235], v[70:73]
	v_mfma_f32_16x16x32_bf16 v[66:69], v[200:203], v[232:235], v[66:69]
	s_setprio 0
	s_barrier
	s_mov_b32 m0, s18
	s_add_u32 s24, s86, 0x40080
	ds_read_b128 v[204:207], v141 offset:49152
	ds_read_b128 v[208:211], v141 offset:50176
	ds_read_b128 v[212:215], v141 offset:51200
	ds_read_b128 v[216:219], v141 offset:52224
	ds_read_b128 v[220:223], v141 offset:53248
	ds_read_b128 v[224:227], v141 offset:54272
	ds_read_b128 v[228:231], v141 offset:55296
	ds_read_b128 v[232:235], v141 offset:56320
	global_load_lds_dwordx4 v164, s[86:87]
	s_mov_b32 m0, s19
	s_addc_u32 s25, s87, 0
	global_load_lds_dwordx4 v165, s[86:87]
	s_mov_b32 m0, s28
	s_nop 0
	global_load_lds_dwordx4 v130, s[24:25]
	s_mov_b32 m0, s57
	s_nop 0
	global_load_lds_dwordx4 v132, s[24:25]
	s_mov_b32 m0, s20
	s_nop 0
	global_load_lds_dwordx4 v164, s[90:91]
	s_mov_b32 m0, s21
	s_nop 0
	global_load_lds_dwordx4 v165, s[90:91]
	s_waitcnt vmcnt(8)
	s_waitcnt lgkmcnt(0)
	s_barrier
	s_setprio 1
	s_waitcnt lgkmcnt(0)
	v_mfma_f32_16x16x32_bf16 v[62:65], v[146:149], v[204:207], v[62:65]
	v_mfma_f32_16x16x32_bf16 v[50:53], v[154:157], v[204:207], v[50:53]
	v_mfma_f32_16x16x32_bf16 v[58:61], v[146:149], v[212:215], v[58:61]
	v_mfma_f32_16x16x32_bf16 v[42:45], v[154:157], v[212:215], v[42:45]
	v_mfma_f32_16x16x32_bf16 v[54:57], v[146:149], v[220:223], v[54:57]
	v_mfma_f32_16x16x32_bf16 v[38:41], v[154:157], v[220:223], v[38:41]
	v_mfma_f32_16x16x32_bf16 v[46:49], v[146:149], v[228:231], v[46:49]
	v_mfma_f32_16x16x32_bf16 v[34:37], v[154:157], v[228:231], v[34:37]
	v_mfma_f32_16x16x32_bf16 v[62:65], v[150:153], v[208:211], v[62:65]
	v_mfma_f32_16x16x32_bf16 v[50:53], v[158:161], v[208:211], v[50:53]
	v_mfma_f32_16x16x32_bf16 v[58:61], v[150:153], v[216:219], v[58:61]
	v_mfma_f32_16x16x32_bf16 v[42:45], v[158:161], v[216:219], v[42:45]
	v_mfma_f32_16x16x32_bf16 v[54:57], v[150:153], v[224:227], v[54:57]
	v_mfma_f32_16x16x32_bf16 v[38:41], v[158:161], v[224:227], v[38:41]
	v_mfma_f32_16x16x32_bf16 v[46:49], v[150:153], v[232:235], v[46:49]
	v_mfma_f32_16x16x32_bf16 v[34:37], v[158:161], v[232:235], v[34:37]
	s_setprio 0
	s_setprio 1
	v_mfma_f32_16x16x32_bf16 v[30:33], v[168:171], v[204:207], v[30:33]
	v_mfma_f32_16x16x32_bf16 v[26:29], v[196:199], v[204:207], v[26:29]
	v_mfma_f32_16x16x32_bf16 v[22:25], v[168:171], v[212:215], v[22:25]
	v_mfma_f32_16x16x32_bf16 v[18:21], v[196:199], v[212:215], v[18:21]
	v_mfma_f32_16x16x32_bf16 v[14:17], v[168:171], v[220:223], v[14:17]
	v_mfma_f32_16x16x32_bf16 v[10:13], v[196:199], v[220:223], v[10:13]
	v_mfma_f32_16x16x32_bf16 v[6:9], v[168:171], v[228:231], v[6:9]
	v_mfma_f32_16x16x32_bf16 v[2:5], v[196:199], v[228:231], v[2:5]
	v_mfma_f32_16x16x32_bf16 v[30:33], v[192:195], v[208:211], v[30:33]
	v_mfma_f32_16x16x32_bf16 v[26:29], v[200:203], v[208:211], v[26:29]
	v_mfma_f32_16x16x32_bf16 v[22:25], v[192:195], v[216:219], v[22:25]
	v_mfma_f32_16x16x32_bf16 v[18:21], v[200:203], v[216:219], v[18:21]
	v_mfma_f32_16x16x32_bf16 v[14:17], v[192:195], v[224:227], v[14:17]
	v_mfma_f32_16x16x32_bf16 v[10:13], v[200:203], v[224:227], v[10:13]
	v_mfma_f32_16x16x32_bf16 v[6:9], v[192:195], v[232:235], v[6:9]
	v_mfma_f32_16x16x32_bf16 v[2:5], v[200:203], v[232:235], v[2:5]
	s_setprio 0
	s_barrier
	s_add_i32 s69, s69, 2
	s_add_u32 s50, s50, 0x100
	s_addc_u32 s51, s51, 0
	s_cmp_gt_u32 s69, 13
	s_mov_b64 s[38:39], s[40:41]
	s_cbranch_scc0 .LBB0_573
	s_and_b64 vcc, exec, s[42:43]
	s_cbranch_vccz .LBB0_576
	s_barrier
